# G2 epilogue: per-row statistic loads hoisted with counted vmcnt; attention: gating V fragments prefetched before the tile barrier
# speedup vs baseline: 1.0259x; 1.0001x over previous
; #define ATT_QKM(S0, S1, buf, C) do { ATT_QK1(S0, buf, 0, C); ATT_QK1(S1, buf, 1, C); } while (0)
; #define ATT_LOADK2(t, KR_, RR_) do { const int kr_ = ATT_KEYROW(t); KR_ = *(const u32x4*)(Kp + (size_t)(kr_ + skey) * ldk + sch * 8); \
;         if (KIND == 0 && tid < 256) RR_ = *(const u32x4*)(Krp + (size_t)(kr_ + skey_r) * 32 + sch_r * 8); } while (0)
; #define ATT_LOADV2(t, VR_) do { const int kr_ = ATT_KEYROW(t); VR_ = *(const u32x4*)(Vp + (size_t)(kr_ + skey) * ldk + sch * 8); } while (0)
; #define ATT_STOREK2(buf, KR_, RR_) do { LAS unsigned char* b_ = lds + (buf) * ATT_KBUF; *(LAS u32x4*)(b_ + kdst) = KR_; if (KIND == 0 && tid < 256) *(LAS u32x4*)(b_ + rdst) = RR_; } while (0)
; #define ATT_STOREV2(vsl, VR_) do { *(LAS u32x4*)(lds + ATT_VB + (vsl) + vdst) = VR_; } while (0)
; template <int KIND>
; DI void attn_unit(const Frame& F, int qrow0, int head, int ctx_row0, int lat_row0, int ntiles) {
;     ...
;     ATT_LOADK2(0, kreg, rreg); ATT_LOADV2(0, vreg);
;     ATT_STOREK2(0, kreg, rreg); ATT_STOREV2(0, vreg);
;     ATT_LOADK2(1, kreg, rreg); ATT_STOREK2(1, kreg, rreg);
;     __syncthreads();
;     { f32x16 z_; _Pragma("unroll") for (int i = 0; i < 16; ++i) z_[i] = 0.f; ATT_QKM(s0, s1, 0, z_); }
;     {
;         float mx = fmaxf(s0[0], s1[0]);
; #pragma unroll
;         for (int i = 1; i < 16; ++i) mx = fmaxf(mx, fmaxf(s0[i], s1[i]));
;         { auto rr = __builtin_amdgcn_permlane32_swap(__float_as_uint(mx), __float_as_uint(mx), false, false); mx = fmaxf(__uint_as_float(rr[0]), __uint_as_float(rr[1])); }
;         mref = mx;
; #pragma unroll
;         for (int i = 0; i < 16; ++i) { s0[i] -= mx; s1[i] -= mx; }
;     }
;     { const int t = 0; ATT_BODY(t, kreg, vreg, rreg, kreg, vreg, rreg, s0, s1, n0, n1, pfa, pfb, 0, 1); }
;     for (int t2 = 1; t2 < ntiles - 1; t2 += 2) {
.LBB0_362:
	v_lshlrev_b32_e32 v22, 3, v71
	v_lshlrev_b32_e32 v96, 1, v22
	v_lshl_add_u64 v[148:149], s[2:3], 0, v[96:97]
	s_and_b32 s2, s65, 4
	v_and_b32_e32 v23, 0xc0, v72
	v_lshlrev_b32_e32 v24, 1, v68
	v_lshlrev_b32_e32 v25, 3, v68
	s_waitcnt vmcnt(1)
	ds_write_b128 v157, v[114:117]
	s_waitcnt vmcnt(0)
	ds_write_b128 v158, v[16:19] offset:36864
	v_add_lshl_u32 v16, s36, v156, 8
	s_lshl_b32 s2, s2, 5
	v_and_b32_e32 v24, 32, v24
	v_and_b32_e32 v25, 24, v25
	v_lshl_or_b32 v23, v69, 8, v23
	s_waitcnt lgkmcnt(0)
	s_barrier
	v_or3_b32 v16, v16, s2, v146
	v_mov_b32_e32 v17, v97
	v_or3_b32 v163, v23, v24, v25
	v_add_f32_e32 v155, v20, v21
	v_lshl_add_u64 v[152:153], s[14:15], 0, v[16:17]
	v_mov_b64_e32 v[30:31], v[14:15]
	v_and_b32_e32 v147, 63, v68
	v_lshlrev_b32_e32 v160, 3, v69
	v_mul_u32_u24_e32 v161, 0x90, v70
	s_mov_b32 s28, 1
	s_add_i32 s16, s54, -1
	v_lshl_add_u64 v[150:151], s[50:51], 0, v[96:97]
	v_add_u32_e32 v164, 0, v163
	s_add_i32 s22, s54, -3
	s_add_i32 s23, s36, 0xffffff40
	s_sub_i32 s24, s36, 64
	v_or_b32_e32 v165, 64, v156
	s_add_i32 s25, s81, 0xc0
	s_movk_i32 s27, 0x2000
	v_mov_b64_e32 v[28:29], v[12:13]
	v_mov_b64_e32 v[26:27], v[10:11]
	v_mov_b64_e32 v[24:25], v[8:9]
	v_mov_b64_e32 v[22:23], v[6:7]
	v_mov_b64_e32 v[20:21], v[4:5]
	v_mov_b64_e32 v[18:19], v[2:3]
	v_mov_b64_e32 v[16:17], v[0:1]
	s_movk_i32 s85, 0x1ff
	s_mov_b32 s50, 0x1c000
	s_mov_b32 s51, 0xf800000
	s_mov_b32 s31, 0x26000
	s_movk_i32 s30, 0x1f8
	s_brev_b32 s29, 18
	v_add_u32_e32 v250, 0, v164
	ds_read_b64_tr_b16 v[234:235], v250 offset:28672
	ds_read_b64_tr_b16 v[236:237], v250 offset:29184
	ds_read_b64_tr_b16 v[238:239], v250 offset:32768
	ds_read_b64_tr_b16 v[240:241], v250 offset:33280
	ds_read_b64_tr_b16 v[242:243], v250 offset:29696
	ds_read_b64_tr_b16 v[244:245], v250 offset:30208
	ds_read_b64_tr_b16 v[246:247], v250 offset:33792
	ds_read_b64_tr_b16 v[248:249], v250 offset:34304
	s_waitcnt lgkmcnt(0)

; template <int KIND>
; DI void attn_unit(const Frame& F, int qrow0, int head, int ctx_row0, int lat_row0, int ntiles) {
;     ...
;     bf16x8 pfa[2][2], pfb[2][2];
;     f32x16 s0, s1, n0, n1;
.LBB0_365:
	s_cmp_lt_u32 s28, 3
	s_cselect_b32 s2, s43, s23
	v_add_u32_e32 v64, s2, v165
	v_ashrrev_i32_e32 v65, 31, v64
	v_lshlrev_b64 v[64:65], 8, v[64:65]
	v_lshl_add_u64 v[64:65], v[150:151], 0, v[64:65]
	global_load_dwordx4 v[118:121], v[64:65], off
	s_add_i32 s2, s27, 0xffffe000
	s_cmp_lg_u32 s27, 0
	s_cselect_b32 s2, s2, 0x4000
	v_add_u32_e32 v154, s2, v164
	ds_read_b128 v[138:141], v159
	ds_read_b128 v[142:145], v159 offset:32
	ds_read_b128 v[166:169], v159 offset:64
	ds_read_b128 v[170:173], v159 offset:96
	ds_read_b64_tr_b16 v[192:193], v154 offset:34816
	ds_read_b64_tr_b16 v[194:195], v154 offset:35328
	ds_read_b64_tr_b16 v[196:197], v154 offset:35840
	ds_read_b64_tr_b16 v[198:199], v154 offset:36352
	v_mfma_f32_32x32x16_bf16 v[0:15], v[234:237], v[130:133], v[0:15]
	v_xor_b32_e32 v64, 0x80000000, v162
	v_mov_b32_e32 v65, v64
	v_mov_b64_e32 v[66:67], v[64:65]
	v_mov_b64_e32 v[68:69], v[64:65]
	v_mov_b64_e32 v[70:71], v[64:65]
	v_mov_b64_e32 v[72:73], v[64:65]
	v_mov_b64_e32 v[74:75], v[64:65]
	v_mfma_f32_32x32x16_bf16 v[16:31], v[238:241], v[130:133], v[16:31]
	v_mov_b64_e32 v[76:77], v[64:65]
	v_mov_b64_e32 v[78:79], v[64:65]
	v_exp_f32_e32 v36, v36
	v_exp_f32_e32 v37, v37
	v_exp_f32_e32 v130, v48
	v_mfma_f32_32x32x16_bf16 v[0:15], v[242:245], v[134:137], v[0:15]
	v_exp_f32_e32 v48, v32
	v_exp_f32_e32 v131, v49
	v_exp_f32_e32 v49, v33
	v_exp_f32_e32 v132, v50
	v_mfma_f32_32x32x16_bf16 v[16:31], v[246:249], v[134:137], v[16:31]
	v_exp_f32_e32 v50, v34
	v_exp_f32_e32 v133, v51
	v_exp_f32_e32 v51, v35
	v_exp_f32_e32 v34, v42
	s_waitcnt lgkmcnt(7)
	v_mfma_f32_32x32x16_bf16 v[80:95], v[138:141], v[98:101], v[64:79]
	ds_read_b128 v[138:141], v159 offset:4640
	v_exp_f32_e32 v35, v43
	v_exp_f32_e32 v42, v46
	v_exp_f32_e32 v43, v47
	v_exp_f32_e32 v134, v52
	s_waitcnt lgkmcnt(7)
	v_mfma_f32_32x32x16_bf16 v[80:95], v[142:145], v[102:105], v[80:95]
	ds_read_b128 v[142:145], v159 offset:4672
	v_exp_f32_e32 v135, v53
	v_exp_f32_e32 v136, v54
	v_exp_f32_e32 v137, v55
	v_exp_f32_e32 v54, v58
	s_waitcnt lgkmcnt(7)
	v_mfma_f32_32x32x16_bf16 v[80:95], v[166:169], v[106:109], v[80:95]
	ds_read_b128 v[166:169], v159 offset:4704
	v_exp_f32_e32 v55, v59
	v_exp_f32_e32 v52, v38
	v_exp_f32_e32 v53, v39
	v_exp_f32_e32 v38, v56
	s_waitcnt lgkmcnt(7)
	v_mfma_f32_32x32x16_bf16 v[80:95], v[170:173], v[110:113], v[80:95]
	ds_read_b128 v[170:173], v159 offset:4608
	v_exp_f32_e32 v32, v40
	v_exp_f32_e32 v39, v57
	v_exp_f32_e32 v33, v41
	v_exp_f32_e32 v56, v60
	s_waitcnt lgkmcnt(3)
	v_mfma_f32_32x32x16_bf16 v[64:79], v[138:141], v[102:105], v[64:79]
	ds_read_b64_tr_b16 v[138:139], v154 offset:31744
	ds_read_b64_tr_b16 v[140:141], v154 offset:32256
	v_exp_f32_e32 v40, v44
	v_exp_f32_e32 v57, v61
	v_exp_f32_e32 v41, v45
	v_exp_f32_e32 v44, v62
	s_waitcnt lgkmcnt(4)
	v_mfma_f32_32x32x16_bf16 v[64:79], v[142:145], v[106:109], v[64:79]
	ds_read_b64_tr_b16 v[142:143], v154 offset:30720
	ds_read_b64_tr_b16 v[144:145], v154 offset:31232
	v_exp_f32_e32 v45, v63
	v_add_f32_e32 v46, v36, v37
	v_add_f32_e32 v47, v130, v48
	v_add_f32_e32 v46, v131, v46
	v_add_f32_e32 v47, v49, v47
	v_add_f32_e32 v46, v132, v46
	s_waitcnt lgkmcnt(5)
	v_mfma_f32_32x32x16_bf16 v[64:79], v[166:169], v[110:113], v[64:79]
	v_add_f32_e32 v47, v50, v47
	v_add_f32_e32 v46, v133, v46
	v_add_f32_e32 v47, v51, v47
	v_add_f32_e32 v46, v34, v46
	v_add_f32_e32 v47, v35, v47
	v_add_f32_e32 v46, v42, v46
	v_add_f32_e32 v47, v43, v47
	s_waitcnt lgkmcnt(4)
	v_mfma_f32_32x32x16_bf16 v[64:79], v[170:173], v[98:101], v[64:79]
	v_add_f32_e32 v46, v134, v46
	v_add_f32_e32 v47, v135, v47
	v_add_f32_e32 v46, v136, v46
	v_add_f32_e32 v47, v137, v47
	v_add_f32_e32 v46, v54, v46
	v_add_f32_e32 v47, v55, v47
	v_add_f32_e32 v46, v52, v46
	v_mfma_f32_32x32x16_bf16 v[16:31], v[192:195], v[126:129], v[16:31]
	v_add_f32_e32 v47, v53, v47
	v_add_f32_e32 v46, v38, v46
	v_add_f32_e32 v47, v32, v47
	v_add_f32_e32 v46, v39, v46
	v_add_f32_e32 v47, v33, v47
	v_add_f32_e32 v46, v56, v46
	v_add_f32_e32 v47, v40, v47
	v_mfma_f32_32x32x16_bf16 v[16:31], v[196:199], v[122:125], v[16:31]
	v_add_f32_e32 v46, v57, v46
	v_add_f32_e32 v47, v41, v47
	v_add_f32_e32 v46, v44, v46
	v_add_f32_e32 v47, v45, v47
	v_add_f32_e32 v46, v46, v47
	s_waitcnt lgkmcnt(2)
	v_mfma_f32_32x32x16_bf16 v[0:15], v[138:141], v[122:125], v[0:15]
	s_waitcnt lgkmcnt(0)
	v_mfma_f32_32x32x16_bf16 v[0:15], v[142:145], v[126:129], v[0:15]
	v_cmp_lt_f32_e32 vcc, s1, v46
	v_mov_b32_e32 v154, v46
	s_cbranch_vccnz .LBB0_381
	v_cvt_pk_bf16_f32 v130, v130, v131
	v_cvt_pk_bf16_f32 v131, v132, v133
	v_cvt_pk_bf16_f32 v132, v134, v135
	v_cvt_pk_bf16_f32 v133, v136, v137
	v_cvt_pk_bf16_f32 v122, v48, v49
	v_cvt_pk_bf16_f32 v123, v50, v51
	v_cvt_pk_bf16_f32 v124, v36, v37
	v_cvt_pk_bf16_f32 v125, v52, v53
	v_cvt_pk_bf16_f32 v134, v38, v39
	v_cvt_pk_bf16_f32 v135, v54, v55
	v_cvt_pk_bf16_f32 v136, v56, v57
	v_cvt_pk_bf16_f32 v137, v44, v45
	v_cvt_pk_bf16_f32 v126, v32, v33
	v_cvt_pk_bf16_f32 v127, v34, v35
	v_cvt_pk_bf16_f32 v128, v40, v41
	v_cvt_pk_bf16_f32 v129, v42, v43
	v_cndmask_b32_e64 v32, 0, 1, s[20:21]
	v_cmp_ne_u32_e64 s[2:3], 1, v32
	s_andn2_b64 vcc, exec, s[20:21]
	s_cbranch_vccnz .LBB0_368

.LBB0_368:
	s_add_i32 s20, s27, 0x2000
	s_cmpk_lg_i32 s27, 0x4000
	s_cselect_b32 s27, s20, 0
	v_add_u32_e32 v32, s27, v158
	s_waitcnt vmcnt(0)
	ds_write_b128 v32, v[118:121] offset:28672
	s_add_i32 s101, s27, 0xffffe000
	s_cmp_lg_u32 s27, 0
	s_cselect_b32 s101, s101, 0x4000
	v_add_u32_e32 v250, s101, v164
	ds_read_b64_tr_b16 v[234:235], v250 offset:29696
	ds_read_b64_tr_b16 v[236:237], v250 offset:30208
	ds_read_b64_tr_b16 v[238:239], v250 offset:33792
	ds_read_b64_tr_b16 v[240:241], v250 offset:34304
	s_waitcnt lgkmcnt(0)
	s_barrier
	s_cmp_lt_u32 s28, s22
	s_cselect_b64 s[20:21], -1, 0
	s_cmp_ge_u32 s28, s22
	s_cbranch_scc1 .LBB0_370
	global_load_dwordx4 v[114:117], v[152:153], off

; template <int KIND>
; DI void attn_unit(const Frame& F, int qrow0, int head, int ctx_row0, int lat_row0, int ntiles) {
;     ...
;     bf16x8 pfa[2][2], pfb[2][2];
;     f32x16 s0, s1, n0, n1;
.LBB0_372:
	s_add_i32 s2, s27, 0xffffe000
	s_cmp_lg_u32 s27, 0
	s_cselect_b32 s2, s2, 0x4000
	ds_read_b128 v[138:141], v159 offset:14336
	ds_read_b128 v[166:169], v159 offset:14368
	ds_read_b128 v[170:173], v159 offset:14400
	ds_read_b128 v[174:177], v159 offset:14432
	v_mfma_f32_32x32x16_bf16 v[0:15], v[234:237], v[134:137], v[0:15]
	v_xor_b32_e32 v32, 0x80000000, v162
	v_mov_b32_e32 v33, v32
	v_mov_b64_e32 v[34:35], v[32:33]
	v_mov_b64_e32 v[36:37], v[32:33]
	v_mov_b64_e32 v[38:39], v[32:33]
	v_mov_b64_e32 v[40:41], v[32:33]
	v_mov_b64_e32 v[42:43], v[32:33]
	v_mfma_f32_32x32x16_bf16 v[16:31], v[238:241], v[134:137], v[16:31]
	v_mov_b64_e32 v[44:45], v[32:33]
	v_mov_b64_e32 v[46:47], v[32:33]
	v_add_f32_e64 v142, v154, v155
	v_add_f32_e64 v143, v155, v154
	v_add_u32_e32 v143, s2, v164
	ds_read_b64_tr_b16 v[192:193], v143 offset:30720
	ds_read_b64_tr_b16 v[194:195], v143 offset:31232
	ds_read_b64_tr_b16 v[196:197], v143 offset:34816
	ds_read_b64_tr_b16 v[198:199], v143 offset:35328
	ds_read_b64_tr_b16 v[200:201], v143 offset:35840
	ds_read_b64_tr_b16 v[202:203], v143 offset:36352
	v_exp_f32_e32 v80, v80
	v_exp_f32_e32 v64, v64
	v_exp_f32_e32 v81, v81
	v_exp_f32_e32 v65, v65
	v_exp_f32_e32 v82, v82
	s_waitcnt lgkmcnt(9)
	v_mfma_f32_32x32x16_bf16 v[48:63], v[138:141], v[98:101], v[32:47]
	ds_read_b128 v[138:141], v159 offset:18976
	v_exp_f32_e32 v66, v66
	v_exp_f32_e32 v83, v83
	v_exp_f32_e32 v67, v67
	v_exp_f32_e32 v84, v84
	s_waitcnt lgkmcnt(9)
	v_mfma_f32_32x32x16_bf16 v[48:63], v[166:169], v[102:105], v[48:63]
	ds_read_b128 v[166:169], v159 offset:19008
	v_exp_f32_e32 v68, v68
	v_exp_f32_e32 v85, v85
	v_exp_f32_e32 v69, v69
	v_exp_f32_e32 v70, v70
	s_waitcnt lgkmcnt(9)
	v_mfma_f32_32x32x16_bf16 v[48:63], v[170:173], v[106:109], v[48:63]
	ds_read_b128 v[170:173], v159 offset:19040
	v_exp_f32_e32 v71, v71
	v_exp_f32_e32 v72, v72
	v_exp_f32_e32 v73, v73
	v_exp_f32_e32 v74, v74
	s_waitcnt lgkmcnt(9)
	v_mfma_f32_32x32x16_bf16 v[48:63], v[174:177], v[110:113], v[48:63]
	ds_read_b128 v[174:177], v159 offset:18944
	v_exp_f32_e32 v75, v75
	v_exp_f32_e32 v76, v76
	v_exp_f32_e32 v77, v77
	v_exp_f32_e32 v78, v78
	s_waitcnt lgkmcnt(3)
	v_mfma_f32_32x32x16_bf16 v[32:47], v[138:141], v[102:105], v[32:47]
	ds_read_b64_tr_b16 v[138:139], v143 offset:31744
	ds_read_b64_tr_b16 v[140:141], v143 offset:32256
	v_exp_f32_e32 v79, v79
	v_exp_f32_e32 v134, v86
	v_exp_f32_e32 v135, v87
	v_exp_f32_e32 v86, v88
	s_waitcnt lgkmcnt(4)
	v_mfma_f32_32x32x16_bf16 v[32:47], v[166:169], v[106:109], v[32:47]
	ds_read_b64_tr_b16 v[166:167], v143 offset:28672
	ds_read_b64_tr_b16 v[168:169], v143 offset:29184
	v_exp_f32_e32 v87, v89
	v_exp_f32_e32 v88, v90
	v_exp_f32_e32 v89, v91
	v_exp_f32_e32 v90, v92
	s_waitcnt lgkmcnt(5)
	v_mfma_f32_32x32x16_bf16 v[32:47], v[170:173], v[110:113], v[32:47]
	ds_read_b64_tr_b16 v[170:171], v143 offset:32768
	ds_read_b64_tr_b16 v[172:173], v143 offset:33280
	v_exp_f32_e32 v91, v93
	v_exp_f32_e32 v92, v94
	v_exp_f32_e32 v93, v95
	v_add_f32_e32 v94, v80, v64
	s_waitcnt lgkmcnt(6)
	v_mfma_f32_32x32x16_bf16 v[32:47], v[174:177], v[98:101], v[32:47]
	v_add_f32_e32 v95, v81, v65
	v_add_f32_e32 v94, v82, v94
	v_add_f32_e32 v95, v66, v95
	v_add_f32_e32 v94, v83, v94
	v_add_f32_e32 v95, v67, v95
	v_add_f32_e32 v94, v84, v94
	v_add_f32_e32 v95, v68, v95
	v_mfma_f32_32x32x16_bf16 v[0:15], v[192:195], v[122:125], v[0:15]
	v_add_f32_e32 v94, v85, v94
	v_add_f32_e32 v95, v69, v95
	v_add_f32_e32 v94, v70, v94
	v_add_f32_e32 v95, v71, v95
	v_add_f32_e32 v94, v72, v94
	v_add_f32_e32 v95, v73, v95
	v_add_f32_e32 v94, v74, v94
	v_mfma_f32_32x32x16_bf16 v[16:31], v[196:199], v[122:125], v[16:31]
	v_add_f32_e32 v95, v75, v95
	v_add_f32_e32 v94, v76, v94
	v_add_f32_e32 v95, v77, v95
	v_add_f32_e32 v94, v78, v94
	v_add_f32_e32 v95, v79, v95
	v_add_f32_e32 v94, v134, v94
	v_add_f32_e32 v95, v135, v95
	v_mfma_f32_32x32x16_bf16 v[16:31], v[200:203], v[126:129], v[16:31]
	v_add_f32_e32 v94, v86, v94
	v_add_f32_e32 v95, v87, v95
	v_add_f32_e32 v94, v88, v94
	v_add_f32_e32 v95, v89, v95
	v_add_f32_e32 v94, v90, v94
	v_add_f32_e32 v95, v91, v95
	v_add_f32_e32 v94, v92, v94
	s_waitcnt lgkmcnt(4)
	v_mfma_f32_32x32x16_bf16 v[0:15], v[138:141], v[126:129], v[0:15]
	v_add_f32_e32 v95, v93, v95
	v_add_f32_e32 v94, v94, v95
	s_waitcnt lgkmcnt(2)
	v_mfma_f32_32x32x16_bf16 v[0:15], v[166:169], v[130:133], v[0:15]
	s_waitcnt lgkmcnt(0)
	v_mfma_f32_32x32x16_bf16 v[16:31], v[170:173], v[130:133], v[16:31]
	v_cmp_lt_f32_e32 vcc, s1, v94
	s_cbranch_vccnz .LBB0_382
	v_cvt_pk_bf16_f32 v130, v80, v81
	v_cvt_pk_bf16_f32 v131, v82, v83
	v_cvt_pk_bf16_f32 v132, v84, v85
	v_cvt_pk_bf16_f32 v133, v134, v135
	v_cvt_pk_bf16_f32 v126, v64, v65
	v_cvt_pk_bf16_f32 v127, v66, v67
	v_cvt_pk_bf16_f32 v128, v68, v69
	v_cvt_pk_bf16_f32 v129, v70, v71
	v_cvt_pk_bf16_f32 v134, v86, v87
	v_cvt_pk_bf16_f32 v135, v88, v89
	v_cvt_pk_bf16_f32 v136, v90, v91
	v_cvt_pk_bf16_f32 v137, v92, v93
	v_cvt_pk_bf16_f32 v122, v72, v73
	v_cvt_pk_bf16_f32 v123, v74, v75
	v_cvt_pk_bf16_f32 v124, v76, v77
	v_cvt_pk_bf16_f32 v125, v78, v79
	s_mov_b32 s28, s48
	s_andn2_b64 vcc, exec, s[20:21]
	s_cbranch_vccnz .LBB0_375

.LBB0_379:
	v_add_u32_e32 v250, s27, v164
	ds_read_b64_tr_b16 v[234:235], v250 offset:28672
	ds_read_b64_tr_b16 v[236:237], v250 offset:29184
	ds_read_b64_tr_b16 v[238:239], v250 offset:32768
	ds_read_b64_tr_b16 v[240:241], v250 offset:33280
	ds_read_b64_tr_b16 v[242:243], v250 offset:29696
	ds_read_b64_tr_b16 v[244:245], v250 offset:30208
	ds_read_b64_tr_b16 v[246:247], v250 offset:33792
	ds_read_b64_tr_b16 v[248:249], v250 offset:34304
	s_waitcnt lgkmcnt(0)
	s_barrier
	s_cmpk_lg_i32 s27, 0x4000
	v_mov_b32_e32 v143, v94
	s_cselect_b32 s27, s18, 0
	s_mov_b64 s[2:3], 0x8000
	s_addk_i32 s24, 0x80
	s_addk_i32 s25, 0x80
	v_pk_add_f32 v[64:65], v[94:95], v[142:143]
	v_lshl_add_u64 v[152:153], v[152:153], 0, s[2:3]
	s_cmp_lt_u32 s26, s16
	v_add_u32_e32 v165, 0x80, v165
	s_cbranch_scc0 .LBB0_383
	v_mov_b32_e32 v155, v64
	s_mov_b32 s28, s26
	s_branch .LBB0_363

; #define ATT_QKM(S0, S1, buf, C) do { ATT_QK1(S0, buf, 0, C); ATT_QK1(S1, buf, 1, C); } while (0)
; #define ATT_LOADK2(t, KR_, RR_) do { const int kr_ = ATT_KEYROW(t); KR_ = *(const u32x4*)(Kp + (size_t)(kr_ + skey) * ldk + sch * 8); \
;         if (KIND == 0 && tid < 256) RR_ = *(const u32x4*)(Krp + (size_t)(kr_ + skey_r) * 32 + sch_r * 8); } while (0)
; #define ATT_LOADV2(t, VR_) do { const int kr_ = ATT_KEYROW(t); VR_ = *(const u32x4*)(Vp + (size_t)(kr_ + skey) * ldk + sch * 8); } while (0)
; #define ATT_STOREK2(buf, KR_, RR_) do { LAS unsigned char* b_ = lds + (buf) * ATT_KBUF; *(LAS u32x4*)(b_ + kdst) = KR_; if (KIND == 0 && tid < 256) *(LAS u32x4*)(b_ + rdst) = RR_; } while (0)
; #define ATT_STOREV2(vsl, VR_) do { *(LAS u32x4*)(lds + ATT_VB + (vsl) + vdst) = VR_; } while (0)
; template <int KIND>
; DI void attn_unit(const Frame& F, int qrow0, int head, int ctx_row0, int lat_row0, int ntiles) {
;     ...
;     ATT_LOADK2(0, kreg, rreg); ATT_LOADV2(0, vreg);
;     ATT_STOREK2(0, kreg, rreg); ATT_STOREV2(0, vreg);
;     ATT_LOADK2(1, kreg, rreg); ATT_STOREK2(1, kreg, rreg);
;     __syncthreads();
;     { f32x16 z_; _Pragma("unroll") for (int i = 0; i < 16; ++i) z_[i] = 0.f; ATT_QKM(s0, s1, 0, z_); }
;     {
;         float mx = fmaxf(s0[0], s1[0]);
; #pragma unroll
;         for (int i = 1; i < 16; ++i) mx = fmaxf(mx, fmaxf(s0[i], s1[i]));
;         { auto rr = __builtin_amdgcn_permlane32_swap(__float_as_uint(mx), __float_as_uint(mx), false, false); mx = fmaxf(__uint_as_float(rr[0]), __uint_as_float(rr[1])); }
;         mref = mx;
; #pragma unroll
;         for (int i = 0; i < 16; ++i) { s0[i] -= mx; s1[i] -= mx; }
;     }
;     { const int t = 0; ATT_BODY(t, kreg, vreg, rreg, kreg, vreg, rreg, s0, s1, n0, n1, pfa, pfb, 0, 1); }
;     for (int t2 = 1; t2 < ntiles - 1; t2 += 2) {
.LBB0_417:
	s_waitcnt vmcnt(0)
	ds_write_b128 v169, v[130:133] offset:28672
	s_waitcnt lgkmcnt(0)
	s_barrier
	s_add_i32 s25, s54, -1
	v_add_f32_e32 v161, v78, v154
	s_cmp_eq_u32 s25, 3
	s_mov_b32 s27, 0
	s_cbranch_scc1 .LBB0_447
	s_add_i32 s4, s36, 64
	v_lshl_or_b32 v66, s37, 7, v150
	v_add_u32_e32 v64, s4, v162
	v_readlane_b32 s28, v255, 17
	v_lshl_or_b32 v64, v64, 10, v66
	v_mov_b32_e32 v65, v97
	v_readlane_b32 s30, v255, 19
	v_readlane_b32 s31, v255, 20
	v_readlane_b32 s29, v255, 18
	s_brev_b32 s29, 18
	v_lshl_add_u64 v[152:153], s[30:31], 0, v[64:65]
	v_add_u32_e32 v64, s36, v162
	v_lshl_or_b32 v64, v64, 10, v66
	v_lshl_add_u64 v[154:155], s[30:31], 0, v[64:65]
	v_add_u32_e32 v64, s4, v163
	v_readlane_b32 s4, v255, 10
	v_lshl_or_b32 v64, v64, 6, v164
	v_readlane_b32 s5, v255, 11
	s_movk_i32 s30, 0x1f8
	s_mov_b32 s31, 0x26000
	v_lshl_add_u64 v[156:157], s[4:5], 0, v[64:65]
	v_add_u32_e32 v64, s36, v163
	v_readlane_b32 s4, v255, 12
	v_lshl_or_b32 v64, v64, 6, v164
	v_readlane_b32 s5, v255, 13
	s_mov_b32 s28, 3
	s_nop 0
	v_lshl_add_u64 v[158:159], s[4:5], 0, v[64:65]
	v_add_u32_e32 v250, 0x4000, v174
	ds_read_b64_tr_b16 v[234:235], v250 offset:28672
	ds_read_b64_tr_b16 v[236:237], v250 offset:29184
	ds_read_b64_tr_b16 v[238:239], v250 offset:32768
	ds_read_b64_tr_b16 v[240:241], v250 offset:33280
	ds_read_b64_tr_b16 v[242:243], v250 offset:29696
	ds_read_b64_tr_b16 v[244:245], v250 offset:30208
	ds_read_b64_tr_b16 v[246:247], v250 offset:33792
	ds_read_b64_tr_b16 v[248:249], v250 offset:34304
	s_waitcnt lgkmcnt(0)

; template <int KIND>
; DI void attn_unit(const Frame& F, int qrow0, int head, int ctx_row0, int lat_row0, int ntiles) {
;     ...
;     bf16x8 pfa[2][2], pfb[2][2];
;     f32x16 s0, s1, n0, n1;
.LBB0_423:
	v_lshl_add_u64 v[164:165], v[154:155], 0, s[44:45]
	v_add_co_u32_e32 v64, vcc, 0xa300000, v164
	s_add_i32 s4, s27, 0xffffe000
	s_nop 0
	v_addc_co_u32_e32 v65, vcc, 0, v165, vcc
	global_load_dwordx4 v[130:133], v[64:65], off
	s_cmp_lg_u32 s27, 0
	s_cselect_b32 s4, s4, 0x4000
	v_add_u32_e32 v160, s4, v174
	ds_read_b128 v[188:191], v170
	ds_read_b128 v[192:195], v170 offset:32
	ds_read_b128 v[196:199], v170 offset:64
	ds_read_b128 v[200:203], v170 offset:96
	ds_read_b128 v[204:207], v171 offset:9216
	ds_read_b128 v[208:211], v171 offset:9248
	ds_read_b64_tr_b16 v[226:227], v160 offset:31744
	ds_read_b64_tr_b16 v[228:229], v160 offset:32256
	ds_read_b64_tr_b16 v[230:231], v160 offset:35840
	ds_read_b64_tr_b16 v[232:233], v160 offset:36352
	v_mfma_f32_32x32x16_bf16 v[16:31], v[234:237], v[142:145], v[16:31]
	v_xor_b32_e32 v64, 0x80000000, v172
	v_mov_b32_e32 v65, v64
	v_mov_b64_e32 v[66:67], v[64:65]
	v_mov_b64_e32 v[68:69], v[64:65]
	v_mov_b64_e32 v[70:71], v[64:65]
	v_mov_b64_e32 v[72:73], v[64:65]
	v_mfma_f32_32x32x16_bf16 v[0:15], v[238:241], v[142:145], v[0:15]
	v_mov_b64_e32 v[74:75], v[64:65]
	v_mov_b64_e32 v[76:77], v[64:65]
	v_mov_b64_e32 v[78:79], v[64:65]
	v_exp_f32_e32 v34, v34
	v_exp_f32_e32 v35, v35
	v_mfma_f32_32x32x16_bf16 v[16:31], v[242:245], v[146:149], v[16:31]
	v_exp_f32_e32 v142, v48
	v_exp_f32_e32 v48, v32
	v_exp_f32_e32 v143, v49
	v_mfma_f32_32x32x16_bf16 v[0:15], v[246:249], v[146:149], v[0:15]
	v_exp_f32_e32 v49, v33
	v_exp_f32_e32 v144, v50
	v_exp_f32_e32 v145, v51
	s_waitcnt lgkmcnt(9)
	v_mfma_f32_32x32x16_bf16 v[80:95], v[188:191], v[98:101], v[64:79]
	ds_read_b128 v[188:191], v170 offset:4640
	v_exp_f32_e32 v50, v36
	v_exp_f32_e32 v32, v40
	v_exp_f32_e32 v33, v41
	s_waitcnt lgkmcnt(9)
	v_mfma_f32_32x32x16_bf16 v[80:95], v[192:195], v[102:105], v[80:95]
	ds_read_b128 v[192:195], v170 offset:4672
	v_exp_f32_e32 v40, v46
	v_exp_f32_e32 v41, v47
	v_exp_f32_e32 v51, v37
	s_waitcnt lgkmcnt(9)
	v_mfma_f32_32x32x16_bf16 v[80:95], v[196:199], v[106:109], v[80:95]
	ds_read_b128 v[196:199], v170 offset:4704
	v_exp_f32_e32 v146, v52
	v_exp_f32_e32 v147, v53
	v_exp_f32_e32 v52, v56
	s_waitcnt lgkmcnt(9)
	v_mfma_f32_32x32x16_bf16 v[80:95], v[200:203], v[110:113], v[80:95]
	ds_read_b128 v[200:203], v171 offset:11776
	v_exp_f32_e32 v53, v57
	v_exp_f32_e32 v56, v58
	v_exp_f32_e32 v57, v59
	s_waitcnt lgkmcnt(9)
	v_mfma_f32_32x32x16_bf16 v[80:95], v[204:207], v[114:117], v[80:95]
	ds_read_b128 v[204:207], v171 offset:11808
	v_exp_f32_e32 v148, v54
	v_exp_f32_e32 v54, v38
	v_exp_f32_e32 v149, v55
	s_waitcnt lgkmcnt(9)
	v_mfma_f32_32x32x16_bf16 v[80:95], v[208:211], v[118:121], v[80:95]
	ds_read_b128 v[208:211], v170 offset:4608
	v_exp_f32_e32 v55, v39
	v_exp_f32_e32 v36, v42
	v_exp_f32_e32 v37, v43
	s_waitcnt lgkmcnt(5)
	v_mfma_f32_32x32x16_bf16 v[64:79], v[188:191], v[102:105], v[64:79]
	v_exp_f32_e32 v42, v60
	v_exp_f32_e32 v38, v44
	v_exp_f32_e32 v43, v61
	s_waitcnt lgkmcnt(4)
	v_mfma_f32_32x32x16_bf16 v[64:79], v[192:195], v[106:109], v[64:79]
	v_exp_f32_e32 v39, v45
	v_exp_f32_e32 v44, v62
	v_exp_f32_e32 v45, v63
	s_waitcnt lgkmcnt(3)
	v_mfma_f32_32x32x16_bf16 v[64:79], v[196:199], v[110:113], v[64:79]
	v_add_f32_e32 v46, v34, v35
	v_add_f32_e32 v47, v142, v48
	v_add_f32_e32 v46, v143, v46
	v_add_f32_e32 v47, v49, v47
	v_add_f32_e32 v46, v144, v46
	v_add_f32_e32 v47, v145, v47
	s_waitcnt lgkmcnt(2)
	v_mfma_f32_32x32x16_bf16 v[64:79], v[200:203], v[114:117], v[64:79]
	v_add_f32_e32 v46, v50, v46
	v_add_f32_e32 v47, v32, v47
	v_add_f32_e32 v46, v33, v46
	v_add_f32_e32 v47, v40, v47
	v_add_f32_e32 v46, v41, v46
	v_add_f32_e32 v47, v51, v47
	s_waitcnt lgkmcnt(1)
	v_mfma_f32_32x32x16_bf16 v[64:79], v[204:207], v[118:121], v[64:79]
	ds_read_b64_tr_b16 v[204:205], v160 offset:30720
	ds_read_b64_tr_b16 v[206:207], v160 offset:31232
	v_add_f32_e32 v46, v146, v46
	v_add_f32_e32 v47, v147, v47
	v_add_f32_e32 v46, v52, v46
	v_add_f32_e32 v47, v53, v47
	v_add_f32_e32 v46, v56, v46
	v_add_f32_e32 v47, v57, v47
	s_waitcnt lgkmcnt(2)
	v_mfma_f32_32x32x16_bf16 v[64:79], v[208:211], v[98:101], v[64:79]
	ds_read_b64_tr_b16 v[208:209], v160 offset:34816
	ds_read_b64_tr_b16 v[210:211], v160 offset:35328
	v_add_f32_e32 v46, v148, v46
	v_add_f32_e32 v47, v54, v47
	v_add_f32_e32 v46, v149, v46
	v_add_f32_e32 v47, v55, v47
	v_add_f32_e32 v46, v36, v46
	v_add_f32_e32 v47, v37, v47
	v_mfma_f32_32x32x16_bf16 v[16:31], v[226:229], v[138:141], v[16:31]
	v_add_f32_e32 v46, v42, v46
	v_add_f32_e32 v47, v38, v47
	v_add_f32_e32 v46, v43, v46
	v_add_f32_e32 v47, v39, v47
	v_add_f32_e32 v46, v44, v46
	v_add_f32_e32 v47, v45, v47
	v_mfma_f32_32x32x16_bf16 v[0:15], v[230:233], v[138:141], v[0:15]
	v_add_f32_e32 v46, v46, v47
	s_waitcnt lgkmcnt(2)
	v_mfma_f32_32x32x16_bf16 v[16:31], v[204:207], v[134:137], v[16:31]
	s_waitcnt lgkmcnt(0)
	v_mfma_f32_32x32x16_bf16 v[0:15], v[208:211], v[134:137], v[0:15]
	v_cmp_lt_f32_e32 vcc, s1, v46
	v_mov_b32_e32 v160, v46
	s_cbranch_vccnz .LBB0_445
	v_cvt_pk_bf16_f32 v142, v142, v143
	v_cvt_pk_bf16_f32 v143, v144, v145
	v_cvt_pk_bf16_f32 v144, v146, v147
	v_cvt_pk_bf16_f32 v145, v148, v149
	v_cvt_pk_bf16_f32 v134, v48, v49
	v_cvt_pk_bf16_f32 v135, v34, v35
	v_cvt_pk_bf16_f32 v136, v50, v51
	v_cvt_pk_bf16_f32 v137, v54, v55
	v_cvt_pk_bf16_f32 v146, v52, v53
	v_cvt_pk_bf16_f32 v147, v56, v57
	v_cvt_pk_bf16_f32 v148, v42, v43
	v_cvt_pk_bf16_f32 v149, v44, v45
	v_cvt_pk_bf16_f32 v138, v32, v33
	v_cvt_pk_bf16_f32 v139, v36, v37
	v_cvt_pk_bf16_f32 v140, v38, v39
	v_cvt_pk_bf16_f32 v141, v40, v41
	v_cndmask_b32_e64 v32, 0, 1, s[20:21]
	v_cmp_ne_u32_e64 s[4:5], 1, v32
	s_andn2_b64 vcc, exec, s[20:21]
	s_cbranch_vccnz .LBB0_428

.LBB0_428:
	s_add_i32 s8, s27, 0x2000
	s_cmpk_lg_i32 s27, 0x4000
	s_cselect_b32 s27, s8, 0
	v_add_u32_e32 v32, s27, v169
	s_waitcnt vmcnt(0)
	ds_write_b128 v32, v[130:133] offset:28672
	s_add_i32 s101, s27, 0xffffe000
	s_cmp_lg_u32 s27, 0
	s_cselect_b32 s101, s101, 0x4000
	v_add_u32_e32 v250, s101, v174
	ds_read_b64_tr_b16 v[234:235], v250 offset:28672
	ds_read_b64_tr_b16 v[236:237], v250 offset:29184
	ds_read_b64_tr_b16 v[238:239], v250 offset:32768
	ds_read_b64_tr_b16 v[240:241], v250 offset:33280
	ds_read_b64_tr_b16 v[242:243], v250 offset:29696
	ds_read_b64_tr_b16 v[244:245], v250 offset:30208
	ds_read_b64_tr_b16 v[246:247], v250 offset:33792
	ds_read_b64_tr_b16 v[248:249], v250 offset:34304
	s_waitcnt lgkmcnt(0)
	s_barrier
	s_cmp_lt_u32 s28, s24
	s_cselect_b64 s[20:21], -1, 0
	s_cmp_ge_u32 s28, s24
	s_cbranch_scc1 .LBB0_432
	v_add_co_u32_e32 v32, vcc, 0x9120000, v164
	s_nop 1
	v_addc_co_u32_e32 v33, vcc, 0, v165, vcc
	global_load_dwordx4 v[126:129], v[32:33], off
	s_and_saveexec_b64 s[8:9], s[2:3]
	s_cbranch_execz .LBB0_431
	v_lshl_add_u64 v[32:33], v[158:159], 0, s[44:45]
	global_load_dwordx4 v[122:125], v[32:33], off

; template <int KIND>
; DI void attn_unit(const Frame& F, int qrow0, int head, int ctx_row0, int lat_row0, int ntiles) {
;     ...
;     bf16x8 pfa[2][2], pfb[2][2];
;     f32x16 s0, s1, n0, n1;
.LBB0_434:
	s_add_i32 s4, s27, 0xffffe000
	s_cmp_lg_u32 s27, 0
	s_cselect_b32 s4, s4, 0x4000
	ds_read_b128 v[162:165], v170 offset:14336
	ds_read_b128 v[188:191], v170 offset:14368
	ds_read_b128 v[192:195], v170 offset:14400
	ds_read_b128 v[196:199], v170 offset:14432
	ds_read_b128 v[200:203], v171 offset:23552
	ds_read_b128 v[204:207], v171 offset:23584
	v_mfma_f32_32x32x16_bf16 v[16:31], v[234:237], v[142:145], v[16:31]
	v_xor_b32_e32 v32, 0x80000000, v172
	v_mov_b32_e32 v33, v32
	v_mov_b64_e32 v[34:35], v[32:33]
	v_mov_b64_e32 v[36:37], v[32:33]
	v_mov_b64_e32 v[38:39], v[32:33]
	v_mov_b64_e32 v[40:41], v[32:33]
	v_mfma_f32_32x32x16_bf16 v[0:15], v[238:241], v[142:145], v[0:15]
	v_mov_b64_e32 v[42:43], v[32:33]
	v_mov_b64_e32 v[44:45], v[32:33]
	v_mov_b64_e32 v[46:47], v[32:33]
	v_pk_add_f32 v[160:161], v[160:161], v[160:161] op_sel:[0,1] op_sel_hi:[1,0]
	v_add_u32_e32 v161, s4, v174
	ds_read_b64_tr_b16 v[208:209], v161 offset:31744
	ds_read_b64_tr_b16 v[210:211], v161 offset:32256
	ds_read_b64_tr_b16 v[226:227], v161 offset:35840
	ds_read_b64_tr_b16 v[228:229], v161 offset:36352
	v_exp_f32_e32 v142, v80
	v_mfma_f32_32x32x16_bf16 v[16:31], v[242:245], v[146:149], v[16:31]
	v_exp_f32_e32 v80, v64
	v_exp_f32_e32 v143, v81
	v_exp_f32_e32 v81, v65
	v_mfma_f32_32x32x16_bf16 v[0:15], v[246:249], v[146:149], v[0:15]
	v_exp_f32_e32 v144, v82
	v_exp_f32_e32 v82, v66
	v_exp_f32_e32 v145, v83
	s_waitcnt lgkmcnt(9)
	v_mfma_f32_32x32x16_bf16 v[48:63], v[162:165], v[98:101], v[32:47]
	ds_read_b128 v[162:165], v170 offset:18976
	v_exp_f32_e32 v83, v67
	v_exp_f32_e32 v64, v72
	v_exp_f32_e32 v65, v73
	s_waitcnt lgkmcnt(9)
	v_mfma_f32_32x32x16_bf16 v[48:63], v[188:191], v[102:105], v[48:63]
	ds_read_b128 v[188:191], v170 offset:19008
	v_exp_f32_e32 v72, v78
	v_exp_f32_e32 v73, v79
	v_exp_f32_e32 v146, v84
	s_waitcnt lgkmcnt(9)
	v_mfma_f32_32x32x16_bf16 v[48:63], v[192:195], v[106:109], v[48:63]
	ds_read_b128 v[192:195], v170 offset:19040
	v_exp_f32_e32 v84, v68
	v_exp_f32_e32 v147, v85
	v_exp_f32_e32 v85, v69
	s_waitcnt lgkmcnt(9)
	v_mfma_f32_32x32x16_bf16 v[48:63], v[196:199], v[110:113], v[48:63]
	ds_read_b128 v[196:199], v171 offset:26112
	v_exp_f32_e32 v148, v86
	v_exp_f32_e32 v86, v70
	v_exp_f32_e32 v149, v87
	s_waitcnt lgkmcnt(9)
	v_mfma_f32_32x32x16_bf16 v[48:63], v[200:203], v[114:117], v[48:63]
	ds_read_b128 v[200:203], v171 offset:26144
	v_exp_f32_e32 v87, v71
	v_exp_f32_e32 v70, v88
	v_exp_f32_e32 v71, v89
	s_waitcnt lgkmcnt(9)
	v_mfma_f32_32x32x16_bf16 v[48:63], v[204:207], v[118:121], v[48:63]
	ds_read_b128 v[204:207], v170 offset:18944
	v_exp_f32_e32 v88, v90
	v_exp_f32_e32 v89, v91
	v_exp_f32_e32 v66, v74
	s_waitcnt lgkmcnt(5)
	v_mfma_f32_32x32x16_bf16 v[32:47], v[162:165], v[102:105], v[32:47]
	v_exp_f32_e32 v67, v75
	v_exp_f32_e32 v74, v92
	v_exp_f32_e32 v68, v76
	s_waitcnt lgkmcnt(4)
	v_mfma_f32_32x32x16_bf16 v[32:47], v[188:191], v[106:109], v[32:47]
	v_exp_f32_e32 v75, v93
	v_exp_f32_e32 v69, v77
	v_exp_f32_e32 v76, v94
	s_waitcnt lgkmcnt(3)
	v_mfma_f32_32x32x16_bf16 v[32:47], v[192:195], v[110:113], v[32:47]
	v_exp_f32_e32 v77, v95
	v_add_f32_e32 v78, v142, v80
	v_add_f32_e32 v79, v143, v81
	v_add_f32_e32 v78, v144, v78
	v_add_f32_e32 v79, v82, v79
	s_waitcnt lgkmcnt(2)
	v_mfma_f32_32x32x16_bf16 v[32:47], v[196:199], v[114:117], v[32:47]
	v_add_f32_e32 v78, v145, v78
	v_add_f32_e32 v79, v83, v79
	v_add_f32_e32 v78, v64, v78
	v_add_f32_e32 v79, v65, v79
	v_add_f32_e32 v78, v72, v78
	v_add_f32_e32 v79, v73, v79
	s_waitcnt lgkmcnt(1)
	v_mfma_f32_32x32x16_bf16 v[32:47], v[200:203], v[118:121], v[32:47]
	ds_read_b64_tr_b16 v[200:201], v161 offset:30720
	ds_read_b64_tr_b16 v[202:203], v161 offset:31232
	v_add_f32_e32 v78, v146, v78
	v_add_f32_e32 v79, v84, v79
	v_add_f32_e32 v78, v147, v78
	v_add_f32_e32 v79, v85, v79
	v_add_f32_e32 v78, v148, v78
	v_add_f32_e32 v79, v86, v79
	s_waitcnt lgkmcnt(2)
	v_mfma_f32_32x32x16_bf16 v[32:47], v[204:207], v[98:101], v[32:47]
	ds_read_b64_tr_b16 v[204:205], v161 offset:34816
	ds_read_b64_tr_b16 v[206:207], v161 offset:35328
	v_add_f32_e32 v78, v149, v78
	v_add_f32_e32 v79, v87, v79
	v_add_f32_e32 v78, v70, v78
	v_add_f32_e32 v79, v71, v79
	v_add_f32_e32 v78, v88, v78
	v_add_f32_e32 v79, v89, v79
	v_mfma_f32_32x32x16_bf16 v[16:31], v[208:211], v[138:141], v[16:31]
	v_add_f32_e32 v78, v66, v78
	v_add_f32_e32 v79, v67, v79
	v_add_f32_e32 v78, v74, v78
	v_add_f32_e32 v79, v68, v79
	v_add_f32_e32 v78, v75, v78
	v_add_f32_e32 v79, v69, v79
	v_mfma_f32_32x32x16_bf16 v[0:15], v[226:229], v[138:141], v[0:15]
	v_add_f32_e32 v78, v76, v78
	v_add_f32_e32 v79, v77, v79
	v_add_f32_e32 v78, v78, v79
	s_waitcnt lgkmcnt(2)
	v_mfma_f32_32x32x16_bf16 v[16:31], v[200:203], v[134:137], v[16:31]
	s_waitcnt lgkmcnt(0)
	v_mfma_f32_32x32x16_bf16 v[0:15], v[204:207], v[134:137], v[0:15]
	v_cmp_lt_f32_e32 vcc, s1, v78
	s_cbranch_vccnz .LBB0_446
	v_cvt_pk_bf16_f32 v142, v142, v143
	v_cvt_pk_bf16_f32 v143, v144, v145
	v_cvt_pk_bf16_f32 v144, v146, v147
	v_cvt_pk_bf16_f32 v145, v148, v149
	v_cvt_pk_bf16_f32 v134, v80, v81
	v_cvt_pk_bf16_f32 v135, v82, v83
	v_cvt_pk_bf16_f32 v136, v84, v85
	v_cvt_pk_bf16_f32 v137, v86, v87
	v_cvt_pk_bf16_f32 v146, v70, v71
	v_cvt_pk_bf16_f32 v147, v88, v89
	v_cvt_pk_bf16_f32 v148, v74, v75
	v_cvt_pk_bf16_f32 v149, v76, v77
	v_cvt_pk_bf16_f32 v138, v64, v65
	v_cvt_pk_bf16_f32 v139, v66, v67
	v_cvt_pk_bf16_f32 v140, v68, v69
	v_cvt_pk_bf16_f32 v141, v72, v73
	s_andn2_b64 vcc, exec, s[20:21]
	s_cbranch_vccnz .LBB0_439

.LBB0_443:
	v_add_u32_e32 v250, s27, v174
	ds_read_b64_tr_b16 v[234:235], v250 offset:28672
	ds_read_b64_tr_b16 v[236:237], v250 offset:29184
	ds_read_b64_tr_b16 v[238:239], v250 offset:32768
	ds_read_b64_tr_b16 v[240:241], v250 offset:33280
	ds_read_b64_tr_b16 v[242:243], v250 offset:29696
	ds_read_b64_tr_b16 v[244:245], v250 offset:30208
	ds_read_b64_tr_b16 v[246:247], v250 offset:33792
	ds_read_b64_tr_b16 v[248:249], v250 offset:34304
	s_waitcnt lgkmcnt(0)
	s_barrier
	s_cmpk_lg_i32 s27, 0x4000
	v_add_f32_e32 v161, v78, v160
	s_cselect_b32 s27, s8, 0
	v_lshl_add_u64 v[152:153], v[152:153], 0, s[74:75]
	v_lshl_add_u64 v[154:155], v[154:155], 0, s[74:75]
	v_lshl_add_u64 v[156:157], v[156:157], 0, s[76:77]
	s_cmp_lt_u32 s26, s25
	v_lshl_add_u64 v[158:159], v[158:159], 0, s[76:77]
	s_cbranch_scc0 .LBB0_447
	s_mov_b32 s28, s26
	s_branch .LBB0_419

; DI u32x4 pk8(const f32x4& a, const f32x4& b) { u32x4 w; w.x = pk2(a[0], a[1]); w.y = pk2(a[2], a[3]); w.z = pk2(b[0], b[1]); w.w = pk2(b[2], b[3]); return w; }
; #define FOR_AI_M _Pragma("unroll") for (int ai = 0; ai < 2; ++ai) _Pragma("unroll") for (int m = 0; m < 4; ++m)
;     DI void operator()(Acc& acc, const Unit& u, int wr, int wc, int fr, int fq) const {
;         unsigned char* ws = F.ws; const int row0 = u.pm * 256;
;         const float* ss = (const float*)(ws + (u.job == 0 ? WS_SSKV : WS_SSQ));
;         bf16_t* dst; int ld; float sc = 1.f;
;         if (u.job == 0) { dst = (bf16_t*)(ws + (u.pn < 2 ? WS_KN : WS_VM)) + (u.pn & 1) * 256; ld = 512; }
;         else { dst = (bf16_t*)(ws + WS_QM); ld = 768; sc = QS_MLA; }
;         const bool ropet = (u.job == 1 && u.pn == 2);
;         const bool rope = ropet && row0 < ML;
;         const float* rm = (const float*)(ws + WS_ROPEM) + 4 * fq;
;         int colv[2];
; #pragma unroll
;         for (int bj = 0; bj < 2; ++bj) {
;             if (u.job == 0) colv[bj] = EPI_COL8(bj);
;             else if (!ropet) { const int c = u.pn * 256 + EPI_COL8(bj); colv[bj] = (c >> 6) * 96 + (c & 63); }
;             else { const int c = EPI_COL8(bj); colv[bj] = (c >> 5) * 96 + 64 + (c & 31); }
;         }
;         FOR_AI_M { const int r = row0 + EPI_ROWS(ai, m);
;             const f32x4 s4 = *(const f32x4*)(ss + (size_t)r * 4);
;             const float rstd = sc * __builtin_amdgcn_rsqf(((s4[0] + s4[1]) + (s4[2] + s4[3])) * (1.f / 256.f) + EPS);
;             f32x4 cs = {1.f, 1.f, 1.f, 1.f}, sn = {0.f, 0.f, 0.f, 0.f};
;             if (rope) { const float* rr = rm + (size_t)(r & 2047) * 32; cs = *(const f32x4*)rr; sn = *(const f32x4*)(rr + 16); }
; #pragma unroll
;             for (int bj = 0; bj < 2; ++bj) {
;                 const f32x4 x1 = acc[ai][bj][m][0] * rstd, x2 = acc[ai][bj][m][1] * rstd;
;                 f32x4 a = x1, b = x2;
;                 if (ropet) { a = x1 * cs - x2 * sn; b = x1 * sn + x2 * cs; }
;                 *(u32x4*)(dst + (size_t)r * ld + colv[bj]) = pk8(a, b);
;             }
.LBB0_821:
	s_and_b64 s[4:5], s[10:11], exec
	s_mov_b32 s4, 0x300000
	s_cselect_b32 s4, s4, 0x380000
	s_add_u32 s50, s94, s4
	v_lshl_add_u32 v162, s60, 8, v164
	s_addc_u32 s51, s95, 0
	v_ashrrev_i32_e32 v163, 31, v162
	v_lshl_add_u64 v[134:135], v[162:163], 4, s[50:51]
	global_load_dwordx4 v[192:195], v[134:135], off
	global_load_dwordx4 v[196:199], v[134:135], off offset:256
	global_load_dwordx4 v[200:203], v[134:135], off offset:512
	global_load_dwordx4 v[204:207], v[134:135], off offset:768
	global_load_dwordx4 v[208:211], v[134:135], off offset:2048
	global_load_dwordx4 v[226:229], v[134:135], off offset:2304
	global_load_dwordx4 v[230:233], v[134:135], off offset:2560
	global_load_dwordx4 v[234:237], v[134:135], off offset:2816
	s_cmp_eq_u32 s58, 1
	s_cselect_b64 s[4:5], -1, 0
	s_cmp_eq_u32 s59, 2
	s_cselect_b64 s[6:7], -1, 0
	s_and_b64 s[4:5], s[4:5], s[6:7]
	s_cmp_lt_i32 s60, 64
	s_cselect_b64 s[6:7], -1, 0
	s_and_b64 s[58:59], s[4:5], s[6:7]
	v_cndmask_b32_e64 v96, 0, 1, s[58:59]
	v_mov_b32_e32 v134, 0
	v_mov_b32_e32 v130, 1.0
	v_cmp_ne_u32_e64 s[6:7], 1, v96
	s_andn2_b64 vcc, exec, s[58:59]
	v_mov_b32_e32 v136, 1.0
	v_mov_b32_e32 v137, 1.0
	v_mov_b32_e32 v138, 1.0
	v_mov_b32_e32 v139, 1.0
	v_mov_b32_e32 v140, 0
	v_mov_b32_e32 v141, 0
	v_mov_b32_e32 v142, 0
	v_mov_b32_e32 v143, 0
	s_cbranch_vccnz .LBB0_823
	v_lshlrev_b32_e32 v96, 7, v162
	v_and_b32_e32 v96, 0x3e780, v96
	v_lshl_add_u64 v[140:141], v[156:157], 0, v[96:97]
	global_load_dwordx4 v[136:139], v[140:141], off
	s_nop 0
	global_load_dwordx4 v[140:143], v[140:141], off offset:64
	s_waitcnt vmcnt(0)
.LBB0_823:
	s_waitcnt vmcnt(7)
	v_add_f32_e32 v133, v192, v193
	v_add_f32_e32 v135, v194, v195
	v_add_f32_e32 v133, v133, v135
	s_or_b32 s9, s9, s54
	v_fmamk_f32 v133, v133, 0x3b800000, v185
	s_ashr_i32 s9, s9, 6
	v_rsq_f32_e32 v133, v133
	s_mulk_i32 s9, 0x60
	v_add_u32_e32 v96, s9, v166
	s_or_b64 vcc, s[10:11], s[4:5]
	v_cndmask_b32_e32 v146, v96, v132, vcc
	v_add_u32_e32 v96, s9, v169
	v_cndmask_b32_e32 v144, v96, v131, vcc
	v_mul_f32_e32 v96, s8, v133
	v_pk_mul_f32 v[126:127], v[126:127], v[96:97] op_sel_hi:[1,0]
	v_pk_mul_f32 v[128:129], v[128:129], v[96:97] op_sel_hi:[1,0]
	v_pk_mul_f32 v[122:123], v[122:123], v[96:97] op_sel_hi:[1,0]
	v_pk_mul_f32 v[124:125], v[124:125], v[96:97] op_sel_hi:[1,0]
	v_pk_mul_f32 v[176:177], v[122:123], v[140:141]
	v_pk_mul_f32 v[174:175], v[124:125], v[142:143]
	v_pk_mul_f32 v[188:189], v[128:129], v[142:143]
	v_pk_mul_f32 v[190:191], v[126:127], v[140:141]
	v_mad_i64_i32 v[132:133], s[10:11], s30, v162, 0
	v_pk_fma_f32 v[176:177], v[126:127], v[136:137], v[176:177] neg_lo:[0,0,1] neg_hi:[0,0,1]
	v_pk_fma_f32 v[174:175], v[128:129], v[138:139], v[174:175] neg_lo:[0,0,1] neg_hi:[0,0,1]
	v_pk_fma_f32 v[190:191], v[122:123], v[136:137], v[190:191]
	v_pk_fma_f32 v[188:189], v[124:125], v[138:139], v[188:189]
	v_lshl_add_u64 v[132:133], v[132:133], 1, s[42:43]
	v_cndmask_b32_e64 v125, v125, v189, s[4:5]
	v_cndmask_b32_e64 v131, v124, v188, s[4:5]
	v_cndmask_b32_e64 v124, v123, v191, s[4:5]
	v_cndmask_b32_e64 v135, v122, v190, s[4:5]
	v_cndmask_b32_e64 v123, v129, v175, s[4:5]
	v_cndmask_b32_e64 v128, v128, v174, s[4:5]
	v_cndmask_b32_e64 v122, v127, v177, s[4:5]
	v_cndmask_b32_e64 v126, v126, v176, s[4:5]
	v_ashrrev_i32_e32 v147, 31, v146
	v_cvt_pk_bf16_f32 v122, v126, v122
	v_cvt_pk_bf16_f32 v123, v128, v123
	v_cvt_pk_bf16_f32 v124, v135, v124
	v_cvt_pk_bf16_f32 v125, v131, v125
	v_lshl_add_u64 v[126:127], v[146:147], 1, v[132:133]
	v_pk_mul_f32 v[118:119], v[118:119], v[96:97] op_sel_hi:[1,0]
	v_pk_mul_f32 v[120:121], v[120:121], v[96:97] op_sel_hi:[1,0]
	v_pk_mul_f32 v[114:115], v[114:115], v[96:97] op_sel_hi:[1,0]
	v_pk_mul_f32 v[116:117], v[116:117], v[96:97] op_sel_hi:[1,0]
	global_store_dwordx4 v[126:127], v[122:125], off
	v_pk_mul_f32 v[126:127], v[120:121], v[142:143]
	v_pk_mul_f32 v[128:129], v[118:119], v[140:141]
	v_pk_mul_f32 v[122:123], v[116:117], v[142:143]
	v_pk_mul_f32 v[124:125], v[114:115], v[140:141]
	v_pk_fma_f32 v[122:123], v[120:121], v[138:139], v[122:123] neg_lo:[0,0,1] neg_hi:[0,0,1]
	v_pk_fma_f32 v[124:125], v[118:119], v[136:137], v[124:125] neg_lo:[0,0,1] neg_hi:[0,0,1]
	v_pk_fma_f32 v[128:129], v[114:115], v[136:137], v[128:129]
	v_pk_fma_f32 v[126:127], v[116:117], v[138:139], v[126:127]
	v_cndmask_b32_e64 v120, v120, v122, s[4:5]
	v_cndmask_b32_e64 v96, v117, v127, s[4:5]
	v_cndmask_b32_e64 v117, v116, v126, s[4:5]
	v_cndmask_b32_e64 v116, v115, v129, s[4:5]
	v_cndmask_b32_e64 v126, v114, v128, s[4:5]
	v_cndmask_b32_e64 v115, v121, v123, s[4:5]
	v_cndmask_b32_e64 v114, v119, v125, s[4:5]
	v_cndmask_b32_e64 v118, v118, v124, s[4:5]
	v_ashrrev_i32_e32 v145, 31, v144
	v_cvt_pk_bf16_f32 v114, v118, v114
	v_cvt_pk_bf16_f32 v115, v120, v115
	v_cvt_pk_bf16_f32 v116, v126, v116
	v_cvt_pk_bf16_f32 v117, v117, v96
	v_lshl_add_u64 v[118:119], v[144:145], 1, v[132:133]
	global_store_dwordx4 v[118:119], v[114:117], off
	v_or_b32_e32 v118, 16, v162
	v_ashrrev_i32_e32 v119, 31, v118
	v_lshl_add_u64 v[114:115], v[118:119], 4, s[50:51]
	s_and_b64 vcc, exec, s[6:7]
	v_mov_b32_e32 v131, 1.0
	v_mov_b32_e32 v132, 1.0
	v_mov_b32_e32 v133, 1.0
	v_mov_b32_e32 v135, 0
	v_mov_b32_e32 v136, 0
	v_mov_b32_e32 v137, 0
	s_mov_b32 s31, 0x26000
	s_cbranch_vccnz .LBB0_825
	v_lshlrev_b32_e32 v96, 7, v118
	v_and_b32_e32 v96, 0x3ef80, v96
	v_lshl_add_u64 v[120:121], v[156:157], 0, v[96:97]
	global_load_dwordx4 v[130:133], v[120:121], off
	global_load_dwordx4 v[134:137], v[120:121], off offset:64
	s_waitcnt vmcnt(0)
; DI u32x4 pk8(const f32x4& a, const f32x4& b) { u32x4 w; w.x = pk2(a[0], a[1]); w.y = pk2(a[2], a[3]); w.z = pk2(b[0], b[1]); w.w = pk2(b[2], b[3]); return w; }
; #define FOR_AI_M _Pragma("unroll") for (int ai = 0; ai < 2; ++ai) _Pragma("unroll") for (int m = 0; m < 4; ++m)
; #define ROW_FENCE asm volatile("" ::: "memory")
;     DI void operator()(Acc& acc, const Unit& u, int wr, int wc, int fr, int fq) const {
;     ...
;         FOR_AI_M { const int r = row0 + EPI_ROWS(ai, m);
;             const f32x4 s4 = *(const f32x4*)(ss + (size_t)r * 4);
;             const float rstd = sc * __builtin_amdgcn_rsqf(((s4[0] + s4[1]) + (s4[2] + s4[3])) * (1.f / 256.f) + EPS);
;             f32x4 cs = {1.f, 1.f, 1.f, 1.f}, sn = {0.f, 0.f, 0.f, 0.f};
;             if (rope) { const float* rr = rm + (size_t)(r & 2047) * 32; cs = *(const f32x4*)rr; sn = *(const f32x4*)(rr + 16); }
; #pragma unroll
;             for (int bj = 0; bj < 2; ++bj) {
;                 const f32x4 x1 = acc[ai][bj][m][0] * rstd, x2 = acc[ai][bj][m][1] * rstd;
;                 f32x4 a = x1, b = x2;
;                 if (ropet) { a = x1 * cs - x2 * sn; b = x1 * sn + x2 * cs; }
;                 *(u32x4*)(dst + (size_t)r * ld + colv[bj]) = pk8(a, b);
;             }
;             if (m & 1) ROW_FENCE;
.LBB0_825:
	s_waitcnt vmcnt(8)
	v_add_f32_e32 v96, v196, v197
	v_add_f32_e32 v114, v198, v199
	v_add_f32_e32 v96, v96, v114
	v_fmamk_f32 v96, v96, 0x3b800000, v185
	v_rsq_f32_e32 v96, v96
	v_mad_i64_i32 v[114:115], s[10:11], s30, v118, 0
	v_lshl_add_u64 v[114:115], v[114:115], 1, s[42:43]
	v_mul_f32_e32 v96, s8, v96
	v_pk_mul_f32 v[110:111], v[110:111], v[96:97] op_sel_hi:[1,0]
	v_pk_mul_f32 v[112:113], v[112:113], v[96:97] op_sel_hi:[1,0]
	v_pk_mul_f32 v[106:107], v[106:107], v[96:97] op_sel_hi:[1,0]
	v_pk_mul_f32 v[108:109], v[108:109], v[96:97] op_sel_hi:[1,0]
	v_pk_mul_f32 v[118:119], v[106:107], v[134:135]
	v_pk_mul_f32 v[116:117], v[108:109], v[136:137]
	v_pk_mul_f32 v[120:121], v[112:113], v[136:137]
	v_pk_mul_f32 v[122:123], v[110:111], v[134:135]
	v_pk_fma_f32 v[118:119], v[110:111], v[130:131], v[118:119] neg_lo:[0,0,1] neg_hi:[0,0,1]
	v_pk_fma_f32 v[116:117], v[112:113], v[132:133], v[116:117] neg_lo:[0,0,1] neg_hi:[0,0,1]
	v_pk_fma_f32 v[122:123], v[106:107], v[130:131], v[122:123]
	v_pk_fma_f32 v[120:121], v[108:109], v[132:133], v[120:121]
	v_cndmask_b32_e64 v112, v112, v116, s[4:5]
	v_cndmask_b32_e64 v109, v109, v121, s[4:5]
	v_cndmask_b32_e64 v120, v108, v120, s[4:5]
	v_cndmask_b32_e64 v108, v107, v123, s[4:5]
	v_cndmask_b32_e64 v121, v106, v122, s[4:5]
	v_cndmask_b32_e64 v107, v113, v117, s[4:5]
	v_cndmask_b32_e64 v106, v111, v119, s[4:5]
	v_cndmask_b32_e64 v110, v110, v118, s[4:5]
	v_cvt_pk_bf16_f32 v106, v110, v106
	v_cvt_pk_bf16_f32 v107, v112, v107
	v_cvt_pk_bf16_f32 v108, v121, v108
	v_cvt_pk_bf16_f32 v109, v120, v109
	v_lshl_add_u64 v[110:111], v[146:147], 1, v[114:115]
	v_pk_mul_f32 v[102:103], v[102:103], v[96:97] op_sel_hi:[1,0]
	v_pk_mul_f32 v[104:105], v[104:105], v[96:97] op_sel_hi:[1,0]
	v_pk_mul_f32 v[98:99], v[98:99], v[96:97] op_sel_hi:[1,0]
	v_pk_mul_f32 v[100:101], v[100:101], v[96:97] op_sel_hi:[1,0]
	global_store_dwordx4 v[110:111], v[106:109], off
	v_pk_mul_f32 v[110:111], v[104:105], v[136:137]
	v_pk_mul_f32 v[112:113], v[102:103], v[134:135]
	v_pk_mul_f32 v[106:107], v[100:101], v[136:137]
	v_pk_mul_f32 v[108:109], v[98:99], v[134:135]
	v_pk_fma_f32 v[106:107], v[104:105], v[132:133], v[106:107] neg_lo:[0,0,1] neg_hi:[0,0,1]
	v_pk_fma_f32 v[108:109], v[102:103], v[130:131], v[108:109] neg_lo:[0,0,1] neg_hi:[0,0,1]
	v_pk_fma_f32 v[112:113], v[98:99], v[130:131], v[112:113]
	v_pk_fma_f32 v[110:111], v[100:101], v[132:133], v[110:111]
	v_cndmask_b32_e64 v104, v104, v106, s[4:5]
	v_cndmask_b32_e64 v96, v101, v111, s[4:5]
	v_cndmask_b32_e64 v101, v100, v110, s[4:5]
	v_cndmask_b32_e64 v100, v99, v113, s[4:5]
	v_cndmask_b32_e64 v110, v98, v112, s[4:5]
	v_cndmask_b32_e64 v99, v105, v107, s[4:5]
	v_cndmask_b32_e64 v98, v103, v109, s[4:5]
	v_cndmask_b32_e64 v102, v102, v108, s[4:5]
	v_cvt_pk_bf16_f32 v98, v102, v98
	v_cvt_pk_bf16_f32 v99, v104, v99
	v_cvt_pk_bf16_f32 v100, v110, v100
	v_cvt_pk_bf16_f32 v101, v101, v96
	v_lshl_add_u64 v[102:103], v[144:145], 1, v[114:115]
	global_store_dwordx4 v[102:103], v[98:101], off
	v_mov_b32_e32 v102, 0
	s_and_b64 vcc, exec, s[6:7]
	v_or_b32_e32 v100, 32, v162
	v_ashrrev_i32_e32 v101, 31, v100
	v_lshl_add_u64 v[98:99], v[100:101], 4, s[50:51]
	v_mov_b32_e32 v98, 1.0
	v_mov_b32_e32 v104, 1.0
	v_mov_b32_e32 v105, 1.0
	v_mov_b32_e32 v106, 1.0
	v_mov_b32_e32 v107, 1.0
	v_mov_b32_e32 v108, 0
	v_mov_b32_e32 v109, 0
	v_mov_b32_e32 v110, 0
	v_mov_b32_e32 v111, 0
	s_cbranch_vccnz .LBB0_827
	v_lshlrev_b32_e32 v96, 7, v100
	v_and_b32_e32 v96, 0x3f780, v96
	v_lshl_add_u64 v[108:109], v[156:157], 0, v[96:97]
	global_load_dwordx4 v[104:107], v[108:109], off
	s_nop 0
	global_load_dwordx4 v[108:111], v[108:109], off offset:64
	s_waitcnt vmcnt(0)
.LBB0_827:
	s_waitcnt vmcnt(9)
	v_add_f32_e32 v96, v200, v201
	v_add_f32_e32 v99, v202, v203
	v_add_f32_e32 v96, v96, v99
	v_fmamk_f32 v96, v96, 0x3b800000, v185
	v_rsq_f32_e32 v96, v96
	v_mad_i64_i32 v[100:101], s[10:11], s30, v100, 0
	v_lshl_add_u64 v[100:101], v[100:101], 1, s[42:43]
	v_mul_f32_e32 v96, s8, v96
	v_pk_mul_f32 v[92:93], v[92:93], v[96:97] op_sel_hi:[1,0]
	v_pk_mul_f32 v[94:95], v[94:95], v[96:97] op_sel_hi:[1,0]
	v_pk_mul_f32 v[88:89], v[88:89], v[96:97] op_sel_hi:[1,0]
	v_pk_mul_f32 v[90:91], v[90:91], v[96:97] op_sel_hi:[1,0]
	v_pk_mul_f32 v[114:115], v[88:89], v[108:109]
	v_pk_mul_f32 v[112:113], v[90:91], v[110:111]
	v_pk_mul_f32 v[116:117], v[94:95], v[110:111]
	v_pk_mul_f32 v[118:119], v[92:93], v[108:109]
	v_pk_fma_f32 v[114:115], v[92:93], v[104:105], v[114:115] neg_lo:[0,0,1] neg_hi:[0,0,1]
	v_pk_fma_f32 v[112:113], v[94:95], v[106:107], v[112:113] neg_lo:[0,0,1] neg_hi:[0,0,1]
	v_pk_fma_f32 v[118:119], v[88:89], v[104:105], v[118:119]
	v_pk_fma_f32 v[116:117], v[90:91], v[106:107], v[116:117]
	v_cndmask_b32_e64 v103, v88, v118, s[4:5]
	v_cndmask_b32_e64 v91, v91, v117, s[4:5]
	v_cndmask_b32_e64 v99, v90, v116, s[4:5]
	v_cndmask_b32_e64 v90, v89, v119, s[4:5]
	v_cndmask_b32_e64 v89, v95, v113, s[4:5]
	v_cndmask_b32_e64 v94, v94, v112, s[4:5]
	v_cndmask_b32_e64 v88, v93, v115, s[4:5]
	v_cndmask_b32_e64 v92, v92, v114, s[4:5]
	v_cvt_pk_bf16_f32 v88, v92, v88
	v_cvt_pk_bf16_f32 v89, v94, v89
	v_cvt_pk_bf16_f32 v90, v103, v90
	v_cvt_pk_bf16_f32 v91, v99, v91
	v_lshl_add_u64 v[92:93], v[146:147], 1, v[100:101]
	v_pk_mul_f32 v[84:85], v[84:85], v[96:97] op_sel_hi:[1,0]
	v_pk_mul_f32 v[86:87], v[86:87], v[96:97] op_sel_hi:[1,0]
	v_pk_mul_f32 v[80:81], v[80:81], v[96:97] op_sel_hi:[1,0]
	v_pk_mul_f32 v[82:83], v[82:83], v[96:97] op_sel_hi:[1,0]
	global_store_dwordx4 v[92:93], v[88:91], off
	v_pk_mul_f32 v[92:93], v[86:87], v[110:111]
	v_pk_mul_f32 v[94:95], v[84:85], v[108:109]
	v_pk_mul_f32 v[88:89], v[82:83], v[110:111]
	v_pk_mul_f32 v[90:91], v[80:81], v[108:109]
	v_pk_fma_f32 v[88:89], v[86:87], v[106:107], v[88:89] neg_lo:[0,0,1] neg_hi:[0,0,1]
	v_pk_fma_f32 v[90:91], v[84:85], v[104:105], v[90:91] neg_lo:[0,0,1] neg_hi:[0,0,1]
	v_pk_fma_f32 v[94:95], v[80:81], v[104:105], v[94:95]
	v_pk_fma_f32 v[92:93], v[82:83], v[106:107], v[92:93]
	v_cndmask_b32_e64 v86, v86, v88, s[4:5]
	v_cndmask_b32_e64 v83, v83, v93, s[4:5]
	v_cndmask_b32_e64 v92, v82, v92, s[4:5]
	v_cndmask_b32_e64 v82, v81, v95, s[4:5]
	v_cndmask_b32_e64 v93, v80, v94, s[4:5]
	v_cndmask_b32_e64 v81, v87, v89, s[4:5]
	v_cndmask_b32_e64 v80, v85, v91, s[4:5]
	v_cndmask_b32_e64 v84, v84, v90, s[4:5]
	v_cvt_pk_bf16_f32 v80, v84, v80
	v_cvt_pk_bf16_f32 v81, v86, v81
	v_cvt_pk_bf16_f32 v82, v93, v82
	v_cvt_pk_bf16_f32 v83, v92, v83
	v_lshl_add_u64 v[84:85], v[144:145], 1, v[100:101]
	global_store_dwordx4 v[84:85], v[80:83], off
	v_or_b32_e32 v84, 48, v162
	v_ashrrev_i32_e32 v85, 31, v84
	v_lshl_add_u64 v[80:81], v[84:85], 4, s[50:51]
	s_and_b64 vcc, exec, s[6:7]
	v_mov_b32_e32 v99, 1.0
	v_mov_b32_e32 v100, 1.0
	v_mov_b32_e32 v101, 1.0
	v_mov_b32_e32 v103, 0
	v_mov_b32_e32 v104, 0
	v_mov_b32_e32 v105, 0
	s_cbranch_vccnz .LBB0_829
; DI u32x4 pk8(const f32x4& a, const f32x4& b) { u32x4 w; w.x = pk2(a[0], a[1]); w.y = pk2(a[2], a[3]); w.z = pk2(b[0], b[1]); w.w = pk2(b[2], b[3]); return w; }
; #define FOR_AI_M _Pragma("unroll") for (int ai = 0; ai < 2; ++ai) _Pragma("unroll") for (int m = 0; m < 4; ++m)
; #define ROW_FENCE asm volatile("" ::: "memory")
;     DI void operator()(Acc& acc, const Unit& u, int wr, int wc, int fr, int fq) const {
;     ...
;         FOR_AI_M { const int r = row0 + EPI_ROWS(ai, m);
;             const f32x4 s4 = *(const f32x4*)(ss + (size_t)r * 4);
;             const float rstd = sc * __builtin_amdgcn_rsqf(((s4[0] + s4[1]) + (s4[2] + s4[3])) * (1.f / 256.f) + EPS);
;             f32x4 cs = {1.f, 1.f, 1.f, 1.f}, sn = {0.f, 0.f, 0.f, 0.f};
;             if (rope) { const float* rr = rm + (size_t)(r & 2047) * 32; cs = *(const f32x4*)rr; sn = *(const f32x4*)(rr + 16); }
; #pragma unroll
;             for (int bj = 0; bj < 2; ++bj) {
;                 const f32x4 x1 = acc[ai][bj][m][0] * rstd, x2 = acc[ai][bj][m][1] * rstd;
;                 f32x4 a = x1, b = x2;
;                 if (ropet) { a = x1 * cs - x2 * sn; b = x1 * sn + x2 * cs; }
;                 *(u32x4*)(dst + (size_t)r * ld + colv[bj]) = pk8(a, b);
;             }
;             if (m & 1) ROW_FENCE;
	v_lshlrev_b32_e32 v85, 7, v84
	v_and_b32_e32 v96, 0x3ff80, v85
	v_lshl_add_u64 v[86:87], v[156:157], 0, v[96:97]
	global_load_dwordx4 v[98:101], v[86:87], off
	global_load_dwordx4 v[102:105], v[86:87], off offset:64
	s_waitcnt vmcnt(0)
.LBB0_829:
	s_waitcnt vmcnt(10)
	v_add_f32_e32 v80, v204, v205
	v_add_f32_e32 v81, v206, v207
	v_add_f32_e32 v80, v80, v81
	v_fmamk_f32 v80, v80, 0x3b800000, v185
	v_rsq_f32_e32 v82, v80
	v_mad_i64_i32 v[80:81], s[10:11], s30, v84, 0
	v_lshl_add_u64 v[80:81], v[80:81], 1, s[42:43]
	v_mul_f32_e32 v82, s8, v82
	v_pk_mul_f32 v[76:77], v[76:77], v[82:83] op_sel_hi:[1,0]
	v_pk_mul_f32 v[78:79], v[78:79], v[82:83] op_sel_hi:[1,0]
	v_pk_mul_f32 v[72:73], v[72:73], v[82:83] op_sel_hi:[1,0]
	v_pk_mul_f32 v[74:75], v[74:75], v[82:83] op_sel_hi:[1,0]
	v_pk_mul_f32 v[86:87], v[72:73], v[102:103]
	v_pk_mul_f32 v[84:85], v[74:75], v[104:105]
	v_pk_mul_f32 v[88:89], v[78:79], v[104:105]
	v_pk_mul_f32 v[90:91], v[76:77], v[102:103]
	v_pk_fma_f32 v[86:87], v[76:77], v[98:99], v[86:87] neg_lo:[0,0,1] neg_hi:[0,0,1]
	v_pk_fma_f32 v[84:85], v[78:79], v[100:101], v[84:85] neg_lo:[0,0,1] neg_hi:[0,0,1]
	v_pk_fma_f32 v[90:91], v[72:73], v[98:99], v[90:91]
	v_pk_fma_f32 v[88:89], v[74:75], v[100:101], v[88:89]
	v_cndmask_b32_e64 v78, v78, v84, s[4:5]
	v_cndmask_b32_e64 v75, v75, v89, s[4:5]
	v_cndmask_b32_e64 v83, v74, v88, s[4:5]
	v_cndmask_b32_e64 v74, v73, v91, s[4:5]
	v_cndmask_b32_e64 v88, v72, v90, s[4:5]
	v_cndmask_b32_e64 v73, v79, v85, s[4:5]
	v_cndmask_b32_e64 v72, v77, v87, s[4:5]
	v_cndmask_b32_e64 v76, v76, v86, s[4:5]
	v_cvt_pk_bf16_f32 v72, v76, v72
	v_cvt_pk_bf16_f32 v73, v78, v73
	v_cvt_pk_bf16_f32 v74, v88, v74
	v_cvt_pk_bf16_f32 v75, v83, v75
	v_lshl_add_u64 v[76:77], v[146:147], 1, v[80:81]
	v_pk_mul_f32 v[68:69], v[68:69], v[82:83] op_sel_hi:[1,0]
	v_pk_mul_f32 v[70:71], v[70:71], v[82:83] op_sel_hi:[1,0]
	v_pk_mul_f32 v[64:65], v[64:65], v[82:83] op_sel_hi:[1,0]
	v_pk_mul_f32 v[66:67], v[66:67], v[82:83] op_sel_hi:[1,0]
	global_store_dwordx4 v[76:77], v[72:75], off
	v_pk_mul_f32 v[76:77], v[70:71], v[104:105]
	v_pk_mul_f32 v[78:79], v[68:69], v[102:103]
	v_pk_mul_f32 v[72:73], v[66:67], v[104:105]
	v_pk_mul_f32 v[74:75], v[64:65], v[102:103]
	v_pk_fma_f32 v[72:73], v[70:71], v[100:101], v[72:73] neg_lo:[0,0,1] neg_hi:[0,0,1]
	v_pk_fma_f32 v[74:75], v[68:69], v[98:99], v[74:75] neg_lo:[0,0,1] neg_hi:[0,0,1]
	v_pk_fma_f32 v[78:79], v[64:65], v[98:99], v[78:79]
	v_pk_fma_f32 v[76:77], v[66:67], v[100:101], v[76:77]
	v_cndmask_b32_e64 v70, v70, v72, s[4:5]
	v_cndmask_b32_e64 v67, v67, v77, s[4:5]
	v_cndmask_b32_e64 v76, v66, v76, s[4:5]
	v_cndmask_b32_e64 v66, v65, v79, s[4:5]
	v_cndmask_b32_e64 v77, v64, v78, s[4:5]
	v_cndmask_b32_e64 v65, v71, v73, s[4:5]
	v_cndmask_b32_e64 v64, v69, v75, s[4:5]
	v_cndmask_b32_e64 v68, v68, v74, s[4:5]
	v_cvt_pk_bf16_f32 v64, v68, v64
	v_cvt_pk_bf16_f32 v65, v70, v65
	v_cvt_pk_bf16_f32 v66, v77, v66
	v_cvt_pk_bf16_f32 v67, v76, v67
	v_lshl_add_u64 v[68:69], v[144:145], 1, v[80:81]
	global_store_dwordx4 v[68:69], v[64:67], off
	v_mov_b32_e32 v68, 0
	s_and_b64 vcc, exec, s[6:7]
	v_add_u32_e32 v66, 0x80, v162
	v_ashrrev_i32_e32 v67, 31, v66
	v_lshl_add_u64 v[64:65], v[66:67], 4, s[50:51]
	v_mov_b32_e32 v64, 1.0
	v_mov_b32_e32 v70, 1.0
	v_mov_b32_e32 v71, 1.0
	v_mov_b32_e32 v72, 1.0
	v_mov_b32_e32 v73, 1.0
	v_mov_b32_e32 v74, 0
	v_mov_b32_e32 v75, 0
	v_mov_b32_e32 v76, 0
	v_mov_b32_e32 v77, 0
	s_cbranch_vccnz .LBB0_831
	v_lshlrev_b32_e32 v65, 7, v66
	v_and_b32_e32 v96, 0x3e780, v65
	v_lshl_add_u64 v[74:75], v[156:157], 0, v[96:97]
	global_load_dwordx4 v[70:73], v[74:75], off
	s_nop 0
	global_load_dwordx4 v[74:77], v[74:75], off offset:64
	s_waitcnt vmcnt(0)
.LBB0_831:
	s_waitcnt vmcnt(11)
	v_add_f32_e32 v65, v208, v209
	v_add_f32_e32 v67, v210, v211
	v_add_f32_e32 v65, v65, v67
	v_fmamk_f32 v65, v65, 0x3b800000, v185
	v_rsq_f32_e32 v65, v65
	v_mad_i64_i32 v[66:67], s[10:11], s30, v66, 0
	v_lshl_add_u64 v[66:67], v[66:67], 1, s[42:43]
	v_mul_f32_e32 v78, s8, v65
	v_pk_mul_f32 v[60:61], v[60:61], v[78:79] op_sel_hi:[1,0]
	v_pk_mul_f32 v[62:63], v[62:63], v[78:79] op_sel_hi:[1,0]
	v_pk_mul_f32 v[56:57], v[56:57], v[78:79] op_sel_hi:[1,0]
	v_pk_mul_f32 v[58:59], v[58:59], v[78:79] op_sel_hi:[1,0]
	v_pk_mul_f32 v[82:83], v[56:57], v[74:75]
	v_pk_mul_f32 v[80:81], v[58:59], v[76:77]
	v_pk_mul_f32 v[84:85], v[62:63], v[76:77]
	v_pk_mul_f32 v[86:87], v[60:61], v[74:75]
	v_pk_fma_f32 v[82:83], v[60:61], v[70:71], v[82:83] neg_lo:[0,0,1] neg_hi:[0,0,1]
	v_pk_fma_f32 v[80:81], v[62:63], v[72:73], v[80:81] neg_lo:[0,0,1] neg_hi:[0,0,1]
	v_pk_fma_f32 v[86:87], v[56:57], v[70:71], v[86:87]
	v_pk_fma_f32 v[84:85], v[58:59], v[72:73], v[84:85]
	v_cndmask_b32_e64 v69, v56, v86, s[4:5]
	v_cndmask_b32_e64 v59, v59, v85, s[4:5]
	v_cndmask_b32_e64 v65, v58, v84, s[4:5]
	v_cndmask_b32_e64 v58, v57, v87, s[4:5]
	v_cndmask_b32_e64 v57, v63, v81, s[4:5]
	v_cndmask_b32_e64 v62, v62, v80, s[4:5]
	v_cndmask_b32_e64 v56, v61, v83, s[4:5]
	v_cndmask_b32_e64 v60, v60, v82, s[4:5]
	v_cvt_pk_bf16_f32 v56, v60, v56
	v_cvt_pk_bf16_f32 v57, v62, v57
	v_cvt_pk_bf16_f32 v58, v69, v58
	v_cvt_pk_bf16_f32 v59, v65, v59
	v_lshl_add_u64 v[60:61], v[146:147], 1, v[66:67]
	v_pk_mul_f32 v[52:53], v[52:53], v[78:79] op_sel_hi:[1,0]
	v_pk_mul_f32 v[54:55], v[54:55], v[78:79] op_sel_hi:[1,0]
	v_pk_mul_f32 v[48:49], v[48:49], v[78:79] op_sel_hi:[1,0]
	v_pk_mul_f32 v[50:51], v[50:51], v[78:79] op_sel_hi:[1,0]
	global_store_dwordx4 v[60:61], v[56:59], off
	v_pk_mul_f32 v[60:61], v[54:55], v[76:77]
	v_pk_mul_f32 v[62:63], v[52:53], v[74:75]
	v_pk_mul_f32 v[56:57], v[50:51], v[76:77]
	v_pk_mul_f32 v[58:59], v[48:49], v[74:75]
	v_pk_fma_f32 v[56:57], v[54:55], v[72:73], v[56:57] neg_lo:[0,0,1] neg_hi:[0,0,1]
	v_pk_fma_f32 v[58:59], v[52:53], v[70:71], v[58:59] neg_lo:[0,0,1] neg_hi:[0,0,1]
	v_pk_fma_f32 v[62:63], v[48:49], v[70:71], v[62:63]
	v_pk_fma_f32 v[60:61], v[50:51], v[72:73], v[60:61]
	v_cndmask_b32_e64 v54, v54, v56, s[4:5]
	v_cndmask_b32_e64 v51, v51, v61, s[4:5]
	v_cndmask_b32_e64 v60, v50, v60, s[4:5]
	v_cndmask_b32_e64 v50, v49, v63, s[4:5]
	v_cndmask_b32_e64 v61, v48, v62, s[4:5]
	v_cndmask_b32_e64 v49, v55, v57, s[4:5]
	v_cndmask_b32_e64 v48, v53, v59, s[4:5]
	v_cndmask_b32_e64 v52, v52, v58, s[4:5]
	v_cvt_pk_bf16_f32 v48, v52, v48
	v_cvt_pk_bf16_f32 v49, v54, v49
	v_cvt_pk_bf16_f32 v50, v61, v50
	v_cvt_pk_bf16_f32 v51, v60, v51
	v_lshl_add_u64 v[52:53], v[144:145], 1, v[66:67]
	global_store_dwordx4 v[52:53], v[48:51], off
	v_add_u32_e32 v52, 0x90, v162
	v_ashrrev_i32_e32 v53, 31, v52
	v_lshl_add_u64 v[48:49], v[52:53], 4, s[50:51]
	s_and_b64 vcc, exec, s[6:7]
	v_mov_b32_e32 v65, 1.0
	v_mov_b32_e32 v66, 1.0
	v_mov_b32_e32 v67, 1.0
	v_mov_b32_e32 v69, 0
	v_mov_b32_e32 v70, 0
	v_mov_b32_e32 v71, 0
	s_cbranch_vccnz .LBB0_833
	v_lshlrev_b32_e32 v53, 7, v52
	v_and_b32_e32 v96, 0x3ef80, v53
	v_lshl_add_u64 v[54:55], v[156:157], 0, v[96:97]
	global_load_dwordx4 v[64:67], v[54:55], off
	global_load_dwordx4 v[68:71], v[54:55], off offset:64
	s_waitcnt vmcnt(0)
; DI u32x4 pk8(const f32x4& a, const f32x4& b) { u32x4 w; w.x = pk2(a[0], a[1]); w.y = pk2(a[2], a[3]); w.z = pk2(b[0], b[1]); w.w = pk2(b[2], b[3]); return w; }
; #define FOR_AI_M _Pragma("unroll") for (int ai = 0; ai < 2; ++ai) _Pragma("unroll") for (int m = 0; m < 4; ++m)
; #define ROW_FENCE asm volatile("" ::: "memory")
;     DI void operator()(Acc& acc, const Unit& u, int wr, int wc, int fr, int fq) const {
;     ...
;         FOR_AI_M { const int r = row0 + EPI_ROWS(ai, m);
;             const f32x4 s4 = *(const f32x4*)(ss + (size_t)r * 4);
;             const float rstd = sc * __builtin_amdgcn_rsqf(((s4[0] + s4[1]) + (s4[2] + s4[3])) * (1.f / 256.f) + EPS);
;             f32x4 cs = {1.f, 1.f, 1.f, 1.f}, sn = {0.f, 0.f, 0.f, 0.f};
;             if (rope) { const float* rr = rm + (size_t)(r & 2047) * 32; cs = *(const f32x4*)rr; sn = *(const f32x4*)(rr + 16); }
; #pragma unroll
;             for (int bj = 0; bj < 2; ++bj) {
;                 const f32x4 x1 = acc[ai][bj][m][0] * rstd, x2 = acc[ai][bj][m][1] * rstd;
;                 f32x4 a = x1, b = x2;
;                 if (ropet) { a = x1 * cs - x2 * sn; b = x1 * sn + x2 * cs; }
;                 *(u32x4*)(dst + (size_t)r * ld + colv[bj]) = pk8(a, b);
;             }
;             if (m & 1) ROW_FENCE;
.LBB0_833:
	s_waitcnt vmcnt(12)
	v_add_f32_e32 v48, v226, v227
	v_add_f32_e32 v49, v228, v229
	v_add_f32_e32 v48, v48, v49
	v_fmamk_f32 v48, v48, 0x3b800000, v185
	v_rsq_f32_e32 v50, v48
	v_mad_i64_i32 v[48:49], s[10:11], s30, v52, 0
	v_lshl_add_u64 v[48:49], v[48:49], 1, s[42:43]
	v_mul_f32_e32 v50, s8, v50
	v_pk_mul_f32 v[44:45], v[44:45], v[50:51] op_sel_hi:[1,0]
	v_pk_mul_f32 v[46:47], v[46:47], v[50:51] op_sel_hi:[1,0]
	v_pk_mul_f32 v[40:41], v[40:41], v[50:51] op_sel_hi:[1,0]
	v_pk_mul_f32 v[42:43], v[42:43], v[50:51] op_sel_hi:[1,0]
	v_pk_mul_f32 v[54:55], v[40:41], v[68:69]
	v_pk_mul_f32 v[52:53], v[42:43], v[70:71]
	v_pk_mul_f32 v[56:57], v[46:47], v[70:71]
	v_pk_mul_f32 v[58:59], v[44:45], v[68:69]
	v_pk_fma_f32 v[54:55], v[44:45], v[64:65], v[54:55] neg_lo:[0,0,1] neg_hi:[0,0,1]
	v_pk_fma_f32 v[52:53], v[46:47], v[66:67], v[52:53] neg_lo:[0,0,1] neg_hi:[0,0,1]
	v_pk_fma_f32 v[58:59], v[40:41], v[64:65], v[58:59]
	v_pk_fma_f32 v[56:57], v[42:43], v[66:67], v[56:57]
	v_cndmask_b32_e64 v46, v46, v52, s[4:5]
	v_cndmask_b32_e64 v43, v43, v57, s[4:5]
	v_cndmask_b32_e64 v51, v42, v56, s[4:5]
	v_cndmask_b32_e64 v42, v41, v59, s[4:5]
	v_cndmask_b32_e64 v56, v40, v58, s[4:5]
	v_cndmask_b32_e64 v41, v47, v53, s[4:5]
	v_cndmask_b32_e64 v40, v45, v55, s[4:5]
	v_cndmask_b32_e64 v44, v44, v54, s[4:5]
	v_cvt_pk_bf16_f32 v40, v44, v40
	v_cvt_pk_bf16_f32 v41, v46, v41
	v_cvt_pk_bf16_f32 v42, v56, v42
	v_cvt_pk_bf16_f32 v43, v51, v43
	v_lshl_add_u64 v[44:45], v[146:147], 1, v[48:49]
	v_pk_mul_f32 v[36:37], v[36:37], v[50:51] op_sel_hi:[1,0]
	v_pk_mul_f32 v[38:39], v[38:39], v[50:51] op_sel_hi:[1,0]
	v_pk_mul_f32 v[32:33], v[32:33], v[50:51] op_sel_hi:[1,0]
	v_pk_mul_f32 v[34:35], v[34:35], v[50:51] op_sel_hi:[1,0]
	global_store_dwordx4 v[44:45], v[40:43], off
	v_pk_mul_f32 v[44:45], v[38:39], v[70:71]
	v_pk_mul_f32 v[46:47], v[36:37], v[68:69]
	v_pk_mul_f32 v[40:41], v[34:35], v[70:71]
	v_pk_mul_f32 v[42:43], v[32:33], v[68:69]
	v_pk_fma_f32 v[40:41], v[38:39], v[66:67], v[40:41] neg_lo:[0,0,1] neg_hi:[0,0,1]
	v_pk_fma_f32 v[42:43], v[36:37], v[64:65], v[42:43] neg_lo:[0,0,1] neg_hi:[0,0,1]
	v_pk_fma_f32 v[46:47], v[32:33], v[64:65], v[46:47]
	v_pk_fma_f32 v[44:45], v[34:35], v[66:67], v[44:45]
	v_cndmask_b32_e64 v38, v38, v40, s[4:5]
	v_cndmask_b32_e64 v35, v35, v45, s[4:5]
	v_cndmask_b32_e64 v44, v34, v44, s[4:5]
	v_cndmask_b32_e64 v34, v33, v47, s[4:5]
	v_cndmask_b32_e64 v45, v32, v46, s[4:5]
	v_cndmask_b32_e64 v33, v39, v41, s[4:5]
	v_cndmask_b32_e64 v32, v37, v43, s[4:5]
	v_cndmask_b32_e64 v36, v36, v42, s[4:5]
	v_cvt_pk_bf16_f32 v32, v36, v32
	v_cvt_pk_bf16_f32 v33, v38, v33
	v_cvt_pk_bf16_f32 v34, v45, v34
	v_cvt_pk_bf16_f32 v35, v44, v35
	v_lshl_add_u64 v[36:37], v[144:145], 1, v[48:49]
	global_store_dwordx4 v[36:37], v[32:35], off
	v_mov_b32_e32 v36, 0
	s_and_b64 vcc, exec, s[6:7]
	v_add_u32_e32 v34, 0xa0, v162
	v_ashrrev_i32_e32 v35, 31, v34
	v_lshl_add_u64 v[32:33], v[34:35], 4, s[50:51]
	v_mov_b32_e32 v32, 1.0
	v_mov_b32_e32 v38, 1.0
	v_mov_b32_e32 v39, 1.0
	v_mov_b32_e32 v40, 1.0
	v_mov_b32_e32 v41, 1.0
	v_mov_b32_e32 v42, 0
	v_mov_b32_e32 v43, 0
	v_mov_b32_e32 v44, 0
	v_mov_b32_e32 v45, 0
	s_cbranch_vccnz .LBB0_835
	v_lshlrev_b32_e32 v33, 7, v34
	v_and_b32_e32 v96, 0x3f780, v33
	v_lshl_add_u64 v[42:43], v[156:157], 0, v[96:97]
	global_load_dwordx4 v[38:41], v[42:43], off
	s_nop 0
	global_load_dwordx4 v[42:45], v[42:43], off offset:64
	s_waitcnt vmcnt(0)
; DI u32x4 pk8(const f32x4& a, const f32x4& b) { u32x4 w; w.x = pk2(a[0], a[1]); w.y = pk2(a[2], a[3]); w.z = pk2(b[0], b[1]); w.w = pk2(b[2], b[3]); return w; }
; #define FOR_AI_M _Pragma("unroll") for (int ai = 0; ai < 2; ++ai) _Pragma("unroll") for (int m = 0; m < 4; ++m)
; #define ROW_FENCE asm volatile("" ::: "memory")
;     DI void operator()(Acc& acc, const Unit& u, int wr, int wc, int fr, int fq) const {
;     ...
;         FOR_AI_M { const int r = row0 + EPI_ROWS(ai, m);
;             const f32x4 s4 = *(const f32x4*)(ss + (size_t)r * 4);
;             const float rstd = sc * __builtin_amdgcn_rsqf(((s4[0] + s4[1]) + (s4[2] + s4[3])) * (1.f / 256.f) + EPS);
;             f32x4 cs = {1.f, 1.f, 1.f, 1.f}, sn = {0.f, 0.f, 0.f, 0.f};
;             if (rope) { const float* rr = rm + (size_t)(r & 2047) * 32; cs = *(const f32x4*)rr; sn = *(const f32x4*)(rr + 16); }
; #pragma unroll
;             for (int bj = 0; bj < 2; ++bj) {
;                 const f32x4 x1 = acc[ai][bj][m][0] * rstd, x2 = acc[ai][bj][m][1] * rstd;
;                 f32x4 a = x1, b = x2;
;                 if (ropet) { a = x1 * cs - x2 * sn; b = x1 * sn + x2 * cs; }
;                 *(u32x4*)(dst + (size_t)r * ld + colv[bj]) = pk8(a, b);
;             }
;             if (m & 1) ROW_FENCE;
.LBB0_835:
	s_waitcnt vmcnt(13)
	v_add_f32_e32 v33, v230, v231
	v_add_f32_e32 v35, v232, v233
	v_add_f32_e32 v33, v33, v35
	v_fmamk_f32 v33, v33, 0x3b800000, v185
	v_rsq_f32_e32 v33, v33
	v_mad_i64_i32 v[34:35], s[10:11], s30, v34, 0
	v_lshl_add_u64 v[34:35], v[34:35], 1, s[42:43]
	v_mul_f32_e32 v46, s8, v33
	v_pk_mul_f32 v[28:29], v[28:29], v[46:47] op_sel_hi:[1,0]
	v_pk_mul_f32 v[30:31], v[30:31], v[46:47] op_sel_hi:[1,0]
	v_pk_mul_f32 v[24:25], v[24:25], v[46:47] op_sel_hi:[1,0]
	v_pk_mul_f32 v[26:27], v[26:27], v[46:47] op_sel_hi:[1,0]
	v_pk_mul_f32 v[50:51], v[24:25], v[42:43]
	v_pk_mul_f32 v[48:49], v[26:27], v[44:45]
	v_pk_mul_f32 v[52:53], v[30:31], v[44:45]
	v_pk_mul_f32 v[54:55], v[28:29], v[42:43]
	v_pk_fma_f32 v[50:51], v[28:29], v[38:39], v[50:51] neg_lo:[0,0,1] neg_hi:[0,0,1]
	v_pk_fma_f32 v[48:49], v[30:31], v[40:41], v[48:49] neg_lo:[0,0,1] neg_hi:[0,0,1]
	v_pk_fma_f32 v[54:55], v[24:25], v[38:39], v[54:55]
	v_pk_fma_f32 v[52:53], v[26:27], v[40:41], v[52:53]
	v_cndmask_b32_e64 v37, v24, v54, s[4:5]
	v_cndmask_b32_e64 v27, v27, v53, s[4:5]
	v_cndmask_b32_e64 v33, v26, v52, s[4:5]
	v_cndmask_b32_e64 v26, v25, v55, s[4:5]
	v_cndmask_b32_e64 v25, v31, v49, s[4:5]
	v_cndmask_b32_e64 v30, v30, v48, s[4:5]
	v_cndmask_b32_e64 v24, v29, v51, s[4:5]
	v_cndmask_b32_e64 v28, v28, v50, s[4:5]
	v_cvt_pk_bf16_f32 v24, v28, v24
	v_cvt_pk_bf16_f32 v25, v30, v25
	v_cvt_pk_bf16_f32 v26, v37, v26
	v_cvt_pk_bf16_f32 v27, v33, v27
	v_lshl_add_u64 v[28:29], v[146:147], 1, v[34:35]
	v_pk_mul_f32 v[20:21], v[20:21], v[46:47] op_sel_hi:[1,0]
	v_pk_mul_f32 v[22:23], v[22:23], v[46:47] op_sel_hi:[1,0]
	v_pk_mul_f32 v[16:17], v[16:17], v[46:47] op_sel_hi:[1,0]
	v_pk_mul_f32 v[18:19], v[18:19], v[46:47] op_sel_hi:[1,0]
	global_store_dwordx4 v[28:29], v[24:27], off
	v_pk_mul_f32 v[28:29], v[22:23], v[44:45]
	v_pk_mul_f32 v[30:31], v[20:21], v[42:43]
	v_pk_mul_f32 v[24:25], v[18:19], v[44:45]
	v_pk_mul_f32 v[26:27], v[16:17], v[42:43]
	v_pk_fma_f32 v[24:25], v[22:23], v[40:41], v[24:25] neg_lo:[0,0,1] neg_hi:[0,0,1]
	v_pk_fma_f32 v[26:27], v[20:21], v[38:39], v[26:27] neg_lo:[0,0,1] neg_hi:[0,0,1]
	v_pk_fma_f32 v[30:31], v[16:17], v[38:39], v[30:31]
	v_pk_fma_f32 v[28:29], v[18:19], v[40:41], v[28:29]
	v_cndmask_b32_e64 v22, v22, v24, s[4:5]
	v_cndmask_b32_e64 v19, v19, v29, s[4:5]
	v_cndmask_b32_e64 v28, v18, v28, s[4:5]
	v_cndmask_b32_e64 v18, v17, v31, s[4:5]
	v_cndmask_b32_e64 v29, v16, v30, s[4:5]
	v_cndmask_b32_e64 v17, v23, v25, s[4:5]
	v_cndmask_b32_e64 v16, v21, v27, s[4:5]
	v_cndmask_b32_e64 v20, v20, v26, s[4:5]
	v_cvt_pk_bf16_f32 v16, v20, v16
	v_cvt_pk_bf16_f32 v17, v22, v17
	v_cvt_pk_bf16_f32 v18, v29, v18
	v_cvt_pk_bf16_f32 v19, v28, v19
	v_lshl_add_u64 v[20:21], v[144:145], 1, v[34:35]
	global_store_dwordx4 v[20:21], v[16:19], off
	v_add_u32_e32 v20, 0xb0, v162
	v_ashrrev_i32_e32 v21, 31, v20
	v_lshl_add_u64 v[16:17], v[20:21], 4, s[50:51]
	s_and_b64 vcc, exec, s[6:7]
	v_mov_b32_e32 v33, 1.0
	v_mov_b32_e32 v34, 1.0
	v_mov_b32_e32 v35, 1.0
	v_mov_b32_e32 v37, 0
	v_mov_b32_e32 v38, 0
	v_mov_b32_e32 v39, 0
	s_cbranch_vccnz .LBB0_837
	v_lshlrev_b32_e32 v21, 7, v20
	v_and_b32_e32 v96, 0x3ff80, v21
	v_lshl_add_u64 v[22:23], v[156:157], 0, v[96:97]
	global_load_dwordx4 v[32:35], v[22:23], off
	global_load_dwordx4 v[36:39], v[22:23], off offset:64
	s_waitcnt vmcnt(0)
.LBB0_837:
	s_waitcnt vmcnt(14)
	v_add_f32_e32 v16, v234, v235
	v_add_f32_e32 v17, v236, v237
	v_mad_i64_i32 v[18:19], s[6:7], s30, v20, 0
	v_add_f32_e32 v16, v16, v17
	v_fmamk_f32 v16, v16, 0x3b800000, v185
	v_rsq_f32_e32 v16, v16
	v_lshl_add_u64 v[18:19], v[18:19], 1, s[42:43]
	s_andn2_b64 vcc, exec, s[2:3]
	s_mov_b64 s[2:3], -1
	v_mul_f32_e32 v16, s8, v16
	v_pk_mul_f32 v[12:13], v[12:13], v[16:17] op_sel_hi:[1,0]
	v_pk_mul_f32 v[14:15], v[14:15], v[16:17] op_sel_hi:[1,0]
	v_pk_mul_f32 v[8:9], v[8:9], v[16:17] op_sel_hi:[1,0]
	v_pk_mul_f32 v[10:11], v[10:11], v[16:17] op_sel_hi:[1,0]
	v_pk_mul_f32 v[22:23], v[8:9], v[36:37]
	v_pk_mul_f32 v[20:21], v[10:11], v[38:39]
	v_pk_mul_f32 v[24:25], v[14:15], v[38:39]
	v_pk_mul_f32 v[26:27], v[12:13], v[36:37]
	v_pk_fma_f32 v[22:23], v[12:13], v[32:33], v[22:23] neg_lo:[0,0,1] neg_hi:[0,0,1]
	v_pk_fma_f32 v[20:21], v[14:15], v[34:35], v[20:21] neg_lo:[0,0,1] neg_hi:[0,0,1]
	v_pk_fma_f32 v[26:27], v[8:9], v[32:33], v[26:27]
	v_pk_fma_f32 v[24:25], v[10:11], v[34:35], v[24:25]
	v_cndmask_b32_e64 v14, v14, v20, s[4:5]
	v_cndmask_b32_e64 v11, v11, v25, s[4:5]
	v_cndmask_b32_e64 v17, v10, v24, s[4:5]
	v_cndmask_b32_e64 v10, v9, v27, s[4:5]
	v_cndmask_b32_e64 v24, v8, v26, s[4:5]
	v_cndmask_b32_e64 v9, v15, v21, s[4:5]
	v_cndmask_b32_e64 v8, v13, v23, s[4:5]
	v_cndmask_b32_e64 v12, v12, v22, s[4:5]
	v_cvt_pk_bf16_f32 v8, v12, v8
	v_cvt_pk_bf16_f32 v9, v14, v9
	v_cvt_pk_bf16_f32 v10, v24, v10
	v_cvt_pk_bf16_f32 v11, v17, v11
	v_lshl_add_u64 v[12:13], v[146:147], 1, v[18:19]
	v_pk_mul_f32 v[4:5], v[4:5], v[16:17] op_sel_hi:[1,0]
	v_pk_mul_f32 v[6:7], v[6:7], v[16:17] op_sel_hi:[1,0]
	v_pk_mul_f32 v[0:1], v[0:1], v[16:17] op_sel_hi:[1,0]
	v_pk_mul_f32 v[2:3], v[2:3], v[16:17] op_sel_hi:[1,0]
	global_store_dwordx4 v[12:13], v[8:11], off
	v_pk_mul_f32 v[12:13], v[6:7], v[38:39]
	v_pk_mul_f32 v[14:15], v[4:5], v[36:37]
	v_pk_mul_f32 v[8:9], v[2:3], v[38:39]
	v_pk_mul_f32 v[10:11], v[0:1], v[36:37]
	v_pk_fma_f32 v[8:9], v[6:7], v[34:35], v[8:9] neg_lo:[0,0,1] neg_hi:[0,0,1]
	v_pk_fma_f32 v[10:11], v[4:5], v[32:33], v[10:11] neg_lo:[0,0,1] neg_hi:[0,0,1]
	v_pk_fma_f32 v[14:15], v[0:1], v[32:33], v[14:15]
	v_pk_fma_f32 v[12:13], v[2:3], v[34:35], v[12:13]
	v_cndmask_b32_e64 v6, v6, v8, s[4:5]
	v_cndmask_b32_e64 v3, v3, v13, s[4:5]
	v_cndmask_b32_e64 v12, v2, v12, s[4:5]
	v_cndmask_b32_e64 v2, v1, v15, s[4:5]
	v_cndmask_b32_e64 v13, v0, v14, s[4:5]
	v_cndmask_b32_e64 v1, v7, v9, s[4:5]
	v_cndmask_b32_e64 v0, v5, v11, s[4:5]
	v_cndmask_b32_e64 v4, v4, v10, s[4:5]
	v_cvt_pk_bf16_f32 v0, v4, v0
	v_cvt_pk_bf16_f32 v1, v6, v1
	v_cvt_pk_bf16_f32 v2, v13, v2
	v_cvt_pk_bf16_f32 v3, v12, v3
	v_lshl_add_u64 v[4:5], v[144:145], 1, v[18:19]
	global_store_dwordx4 v[4:5], v[0:3], off
	s_mov_b32 s50, 0x1c000
	s_mov_b32 s51, 0xf800000
	s_cbranch_vccnz .LBB0_805
	s_andn2_b64 vcc, exec, s[12:13]
	s_cbranch_vccnz .LBB0_804
	s_barrier
	s_branch .LBB0_804
